# P2a in-loop prune rewritten: four queries in lock step (one per 16-lane row), 64-bin histogram with LDS atomics replaced by 6-step bisection over the same bin edges (same thresholds); mixC epilogue lo
# speedup vs baseline: 1.0362x; 1.0362x over previous
.LBB0_615:
	v_mov_b32_e32 v0, s21
	s_waitcnt lgkmcnt(0)
	s_barrier
	ds_read_b32 v0, v0
	s_xor_b64 s[0:1], s[0:1], -1
	s_waitcnt lgkmcnt(0)
	v_cmp_ne_u32_e32 vcc, s9, v0
	s_and_b64 s[0:1], s[0:1], vcc
	s_and_b64 vcc, exec, s[0:1]
	s_cbranch_vccnz .LBB0_1045
	v_and_b32_e32 v58, 15, v66
	v_lshlrev_b32_e32 v41, 4, v58
	v_sub_u32_e32 v40, v195, v41
	v_lshrrev_b32_e32 v57, 4, v66
	v_lshl_add_u32 v59, v57, 11, s33
	v_add_u32_e32 v60, v59, v41
	s_mov_b32 s22, 0
	s_mov_b32 s23, 0
	s_cmpk_gt_i32 s78, 0x140
	s_cselect_b32 s0, 0xffff, 0
	s_or_b32 s22, s22, s0
	s_cmpk_gt_i32 s61, 0x140
	s_cselect_b32 s0, 0xffff0000, 0
	s_or_b32 s22, s22, s0
	s_cmpk_gt_i32 s16, 0x140
	s_cselect_b32 s0, 0xffff, 0
	s_or_b32 s23, s23, s0
	s_cmpk_gt_i32 s15, 0x140
	s_cselect_b32 s0, 0xffff0000, 0
	s_or_b32 s23, s23, s0
	s_cmp_eq_u64 s[22:23], 0
	s_cbranch_scc1 .Lp2apr0_end
	v_mov_b32_e32 v32, s78
	v_mov_b32_e32 v41, s61
	v_mov_b32_e32 v42, s16
	v_mov_b32_e32 v43, s15
	s_nop 0
	v_mov_b32_dpp v32, v41 quad_perm:[0,1,2,3] row_mask:0x2 bank_mask:0xf
	v_mov_b32_dpp v32, v42 quad_perm:[0,1,2,3] row_mask:0x4 bank_mask:0xf
	v_mov_b32_dpp v32, v43 quad_perm:[0,1,2,3] row_mask:0x8 bank_mask:0xf
	v_mov_b32_e32 v33, s73
	v_mov_b32_e32 v41, s72
	v_mov_b32_e32 v42, s71
	v_mov_b32_e32 v43, s70
	s_nop 0
	v_mov_b32_dpp v33, v41 quad_perm:[0,1,2,3] row_mask:0x2 bank_mask:0xf
	v_mov_b32_dpp v33, v42 quad_perm:[0,1,2,3] row_mask:0x4 bank_mask:0xf
	v_mov_b32_dpp v33, v43 quad_perm:[0,1,2,3] row_mask:0x8 bank_mask:0xf
	ds_read_b128 v[0:3], v60
	ds_read_b128 v[4:7], v60 offset:256
	ds_read_b128 v[8:11], v60 offset:512
	ds_read_b128 v[12:15], v60 offset:768
	ds_read_b128 v[16:19], v60 offset:1024
	ds_read_b128 v[20:23], v60 offset:1280
	ds_read_b128 v[24:27], v60 offset:1536
	ds_read_b128 v[28:31], v60 offset:1792
	v_lshlrev_b32_e32 v41, 2, v58
	v_sub_u32_e32 v41, v32, v41
	s_waitcnt lgkmcnt(0)
	v_mov_b32_e32 v47, 20
	v_subrev_u32_e32 v42, 320, v41
	v_med3_i32 v43, v42, 0, 4
	v_add_u32_e32 v47, v47, v43
	v_cmp_lt_i32_e32 vcc, 0, v42
	v_cmp_lt_i32_e64 s[0:1], 1, v42
	v_cmp_lt_i32_e64 s[2:3], 2, v42
	v_cndmask_b32_e32 v20, 0, v20, vcc
	v_cmp_lt_i32_e32 vcc, 3, v42
	v_cndmask_b32_e64 v21, 0, v21, s[0:1]
	v_cndmask_b32_e64 v22, 0, v22, s[2:3]
	v_cndmask_b32_e32 v23, 0, v23, vcc
	v_subrev_u32_e32 v42, 384, v41
	v_med3_i32 v43, v42, 0, 4
	v_add_u32_e32 v47, v47, v43
	v_cmp_lt_i32_e32 vcc, 0, v42
	v_cmp_lt_i32_e64 s[0:1], 1, v42
	v_cmp_lt_i32_e64 s[2:3], 2, v42
	v_cndmask_b32_e32 v24, 0, v24, vcc
	v_cmp_lt_i32_e32 vcc, 3, v42
	v_cndmask_b32_e64 v25, 0, v25, s[0:1]
	v_cndmask_b32_e64 v26, 0, v26, s[2:3]
	v_cndmask_b32_e32 v27, 0, v27, vcc
	v_subrev_u32_e32 v42, 448, v41
	v_med3_i32 v43, v42, 0, 4
	v_add_u32_e32 v47, v47, v43
	v_cmp_lt_i32_e32 vcc, 0, v42
	v_cmp_lt_i32_e64 s[0:1], 1, v42
	v_cmp_lt_i32_e64 s[2:3], 2, v42
	v_cndmask_b32_e32 v28, 0, v28, vcc
	v_cmp_lt_i32_e32 vcc, 3, v42
	v_cndmask_b32_e64 v29, 0, v29, s[0:1]
	v_cndmask_b32_e64 v30, 0, v30, s[2:3]
	v_cndmask_b32_e32 v31, 0, v31, vcc
	v_max3_u32 v35, v0, v1, v2
	v_max3_u32 v35, v3, v4, v35
	v_max3_u32 v35, v5, v6, v35
	v_max3_u32 v35, v7, v8, v35
	v_max3_u32 v35, v9, v10, v35
	v_max3_u32 v35, v11, v12, v35
	v_max3_u32 v35, v13, v14, v35
	v_max3_u32 v35, v15, v16, v35
	v_max3_u32 v35, v17, v18, v35
	v_max3_u32 v35, v19, v20, v35
	v_max3_u32 v35, v21, v22, v35
	v_max3_u32 v35, v23, v24, v35
	v_max3_u32 v35, v25, v26, v35
	v_max3_u32 v35, v27, v28, v35
	v_max3_u32 v35, v29, v30, v35
	v_max_u32_e32 v35, v31, v35
	s_nop 1
	v_max_u32_dpp v35, v35, v35 row_ror:1 row_mask:0xf bank_mask:0xf
	s_nop 1
	v_max_u32_dpp v35, v35, v35 row_ror:2 row_mask:0xf bank_mask:0xf
	s_nop 1
	v_max_u32_dpp v35, v35, v35 row_ror:4 row_mask:0xf bank_mask:0xf
	s_nop 1
	v_max_u32_dpp v35, v35, v35 row_ror:8 row_mask:0xf bank_mask:0xf
	v_and_b32_e32 v34, 0xffffe000, v33
	v_cmp_eq_u32_e32 vcc, 0, v33
	s_and_b64 vcc, vcc, s[22:23]
	s_cbranch_vccz .Lp2apr0_nomin
	v_add_u32_e32 v41, -1, v0
	v_add_u32_e32 v42, -1, v1
	v_min_u32_e32 v43, v41, v42
	v_add_u32_e32 v41, -1, v2
	v_add_u32_e32 v42, -1, v3
	v_min3_u32 v43, v41, v42, v43
	v_add_u32_e32 v41, -1, v4
	v_add_u32_e32 v42, -1, v5
	v_min3_u32 v43, v41, v42, v43
	v_add_u32_e32 v41, -1, v6
	v_add_u32_e32 v42, -1, v7
	v_min3_u32 v43, v41, v42, v43
	v_add_u32_e32 v41, -1, v8
	v_add_u32_e32 v42, -1, v9
	v_min3_u32 v43, v41, v42, v43
	v_add_u32_e32 v41, -1, v10
	v_add_u32_e32 v42, -1, v11
	v_min3_u32 v43, v41, v42, v43
	v_add_u32_e32 v41, -1, v12
	v_add_u32_e32 v42, -1, v13
	v_min3_u32 v43, v41, v42, v43
	v_add_u32_e32 v41, -1, v14
	v_add_u32_e32 v42, -1, v15
	v_min3_u32 v43, v41, v42, v43
	v_add_u32_e32 v41, -1, v16
	v_add_u32_e32 v42, -1, v17
	v_min3_u32 v43, v41, v42, v43
	v_add_u32_e32 v41, -1, v18
	v_add_u32_e32 v42, -1, v19
	v_min3_u32 v43, v41, v42, v43
	v_add_u32_e32 v41, -1, v20
	v_add_u32_e32 v42, -1, v21
	v_min3_u32 v43, v41, v42, v43
	v_add_u32_e32 v41, -1, v22
	v_add_u32_e32 v42, -1, v23
	v_min3_u32 v43, v41, v42, v43
	v_add_u32_e32 v41, -1, v24
	v_add_u32_e32 v42, -1, v25
	v_min3_u32 v43, v41, v42, v43
	v_add_u32_e32 v41, -1, v26
	v_add_u32_e32 v42, -1, v27
	v_min3_u32 v43, v41, v42, v43
	v_add_u32_e32 v41, -1, v28
	v_add_u32_e32 v42, -1, v29
	v_min3_u32 v43, v41, v42, v43
	v_add_u32_e32 v41, -1, v30
	v_add_u32_e32 v42, -1, v31
	v_min3_u32 v43, v41, v42, v43
	s_nop 1
	v_min_u32_dpp v43, v43, v43 row_ror:1 row_mask:0xf bank_mask:0xf
	s_nop 1
	v_min_u32_dpp v43, v43, v43 row_ror:2 row_mask:0xf bank_mask:0xf
	s_nop 1
	v_min_u32_dpp v43, v43, v43 row_ror:4 row_mask:0xf bank_mask:0xf
	s_nop 1
	v_min_u32_dpp v43, v43, v43 row_ror:8 row_mask:0xf bank_mask:0xf
	v_add_u32_e32 v43, 1, v43
	v_cmp_eq_u32_e32 vcc, 0, v33
	s_nop 1
	v_cndmask_b32_e32 v34, v34, v43, vcc
.Lp2apr0_nomin:
	v_mov_b32_e32 v37, v34
	v_mov_b32_e32 v46, v32
	v_mov_b32_e32 v62, v47
	s_not_b64 s[50:51], s[22:23]
.Lp2apr0_iter:
	v_sub_u32_e32 v38, v35, v34
	v_or_b32_e32 v41, 1, v38
	v_ffbh_u32_e32 v41, v41
	v_sub_u32_e32 v41, 26, v41
	v_max_i32_e32 v39, 0, v41
	v_mov_b32_e32 v36, 0
	v_or_b32_e32 v42, 32, v36
	v_lshlrev_b32_e32 v41, v39, v42
	v_add_u32_e64 v43, v34, v41 clamp
	v_mov_b32_e32 v44, 0
	v_cmp_ge_u32_e32 vcc, v0, v43
	v_cmp_ge_u32_e64 s[0:1], v1, v43
	v_cmp_ge_u32_e64 s[2:3], v2, v43
	v_addc_co_u32_e64 v44, vcc, 0, v44, vcc
	v_cmp_ge_u32_e32 vcc, v3, v43
	v_addc_co_u32_e64 v44, s[0:1], 0, v44, s[0:1]
	v_cmp_ge_u32_e64 s[0:1], v4, v43
	v_addc_co_u32_e64 v44, s[2:3], 0, v44, s[2:3]
	v_cmp_ge_u32_e64 s[2:3], v5, v43
	v_addc_co_u32_e64 v44, vcc, 0, v44, vcc
	v_cmp_ge_u32_e32 vcc, v6, v43
	v_addc_co_u32_e64 v44, s[0:1], 0, v44, s[0:1]
	v_cmp_ge_u32_e64 s[0:1], v7, v43
	v_addc_co_u32_e64 v44, s[2:3], 0, v44, s[2:3]
	v_cmp_ge_u32_e64 s[2:3], v8, v43
	v_addc_co_u32_e64 v44, vcc, 0, v44, vcc
	v_cmp_ge_u32_e32 vcc, v9, v43
	v_addc_co_u32_e64 v44, s[0:1], 0, v44, s[0:1]
	v_cmp_ge_u32_e64 s[0:1], v10, v43
	v_addc_co_u32_e64 v44, s[2:3], 0, v44, s[2:3]
	v_cmp_ge_u32_e64 s[2:3], v11, v43
	v_addc_co_u32_e64 v44, vcc, 0, v44, vcc
	v_cmp_ge_u32_e32 vcc, v12, v43
	v_addc_co_u32_e64 v44, s[0:1], 0, v44, s[0:1]
	v_cmp_ge_u32_e64 s[0:1], v13, v43
	v_addc_co_u32_e64 v44, s[2:3], 0, v44, s[2:3]
	v_cmp_ge_u32_e64 s[2:3], v14, v43
	v_addc_co_u32_e64 v44, vcc, 0, v44, vcc
	v_cmp_ge_u32_e32 vcc, v15, v43
	v_addc_co_u32_e64 v44, s[0:1], 0, v44, s[0:1]
	v_cmp_ge_u32_e64 s[0:1], v16, v43
	v_addc_co_u32_e64 v44, s[2:3], 0, v44, s[2:3]
	v_cmp_ge_u32_e64 s[2:3], v17, v43
	v_addc_co_u32_e64 v44, vcc, 0, v44, vcc
	v_cmp_ge_u32_e32 vcc, v18, v43
	v_addc_co_u32_e64 v44, s[0:1], 0, v44, s[0:1]
	v_cmp_ge_u32_e64 s[0:1], v19, v43
	v_addc_co_u32_e64 v44, s[2:3], 0, v44, s[2:3]
	v_cmp_ge_u32_e64 s[2:3], v20, v43
	v_addc_co_u32_e64 v44, vcc, 0, v44, vcc
	v_cmp_ge_u32_e32 vcc, v21, v43
	v_addc_co_u32_e64 v44, s[0:1], 0, v44, s[0:1]
	v_cmp_ge_u32_e64 s[0:1], v22, v43
	v_addc_co_u32_e64 v44, s[2:3], 0, v44, s[2:3]
	v_cmp_ge_u32_e64 s[2:3], v23, v43
	v_addc_co_u32_e64 v44, vcc, 0, v44, vcc
	v_cmp_ge_u32_e32 vcc, v24, v43
	v_addc_co_u32_e64 v44, s[0:1], 0, v44, s[0:1]
	v_cmp_ge_u32_e64 s[0:1], v25, v43
	v_addc_co_u32_e64 v44, s[2:3], 0, v44, s[2:3]
	v_cmp_ge_u32_e64 s[2:3], v26, v43
	v_addc_co_u32_e64 v44, vcc, 0, v44, vcc
	v_cmp_ge_u32_e32 vcc, v27, v43
	v_addc_co_u32_e64 v44, s[0:1], 0, v44, s[0:1]
	v_cmp_ge_u32_e64 s[0:1], v28, v43
	v_addc_co_u32_e64 v44, s[2:3], 0, v44, s[2:3]
	v_cmp_ge_u32_e64 s[2:3], v29, v43
	v_addc_co_u32_e64 v44, vcc, 0, v44, vcc
	v_cmp_ge_u32_e32 vcc, v30, v43
	v_addc_co_u32_e64 v44, s[0:1], 0, v44, s[0:1]
	v_cmp_ge_u32_e64 s[0:1], v31, v43
	v_addc_co_u32_e64 v44, s[2:3], 0, v44, s[2:3]
	v_addc_co_u32_e64 v44, vcc, 0, v44, vcc
	v_addc_co_u32_e64 v44, s[0:1], 0, v44, s[0:1]
	v_mov_b32_e32 v45, v44
	s_nop 1
	v_add_u32_dpp v45, v45, v45 row_ror:1 row_mask:0xf bank_mask:0xf
	s_nop 1
	v_add_u32_dpp v45, v45, v45 row_ror:2 row_mask:0xf bank_mask:0xf
	s_nop 1
	v_add_u32_dpp v45, v45, v45 row_ror:4 row_mask:0xf bank_mask:0xf
	s_nop 1
	v_add_u32_dpp v45, v45, v45 row_ror:8 row_mask:0xf bank_mask:0xf
	s_nop 0
	v_cmp_le_u32_e32 vcc, 0x100, v45
	s_nop 1
	v_cndmask_b32_e32 v36, v36, v42, vcc
	v_cndmask_b32_e32 v46, v46, v45, vcc
	v_cndmask_b32_e32 v47, v47, v44, vcc
	v_or_b32_e32 v42, 16, v36
	v_lshlrev_b32_e32 v41, v39, v42
	v_add_u32_e64 v43, v34, v41 clamp
	v_mov_b32_e32 v44, 0
	v_cmp_ge_u32_e32 vcc, v0, v43
	v_cmp_ge_u32_e64 s[0:1], v1, v43
	v_cmp_ge_u32_e64 s[2:3], v2, v43
	v_addc_co_u32_e64 v44, vcc, 0, v44, vcc
	v_cmp_ge_u32_e32 vcc, v3, v43
	v_addc_co_u32_e64 v44, s[0:1], 0, v44, s[0:1]
	v_cmp_ge_u32_e64 s[0:1], v4, v43
	v_addc_co_u32_e64 v44, s[2:3], 0, v44, s[2:3]
	v_cmp_ge_u32_e64 s[2:3], v5, v43
	v_addc_co_u32_e64 v44, vcc, 0, v44, vcc
	v_cmp_ge_u32_e32 vcc, v6, v43
	v_addc_co_u32_e64 v44, s[0:1], 0, v44, s[0:1]
	v_cmp_ge_u32_e64 s[0:1], v7, v43
	v_addc_co_u32_e64 v44, s[2:3], 0, v44, s[2:3]
	v_cmp_ge_u32_e64 s[2:3], v8, v43
	v_addc_co_u32_e64 v44, vcc, 0, v44, vcc
	v_cmp_ge_u32_e32 vcc, v9, v43
	v_addc_co_u32_e64 v44, s[0:1], 0, v44, s[0:1]
	v_cmp_ge_u32_e64 s[0:1], v10, v43
	v_addc_co_u32_e64 v44, s[2:3], 0, v44, s[2:3]
	v_cmp_ge_u32_e64 s[2:3], v11, v43
	v_addc_co_u32_e64 v44, vcc, 0, v44, vcc
	v_cmp_ge_u32_e32 vcc, v12, v43
	v_addc_co_u32_e64 v44, s[0:1], 0, v44, s[0:1]
	v_cmp_ge_u32_e64 s[0:1], v13, v43
	v_addc_co_u32_e64 v44, s[2:3], 0, v44, s[2:3]
	v_cmp_ge_u32_e64 s[2:3], v14, v43
	v_addc_co_u32_e64 v44, vcc, 0, v44, vcc
	v_cmp_ge_u32_e32 vcc, v15, v43
	v_addc_co_u32_e64 v44, s[0:1], 0, v44, s[0:1]
	v_cmp_ge_u32_e64 s[0:1], v16, v43
	v_addc_co_u32_e64 v44, s[2:3], 0, v44, s[2:3]
	v_cmp_ge_u32_e64 s[2:3], v17, v43
	v_addc_co_u32_e64 v44, vcc, 0, v44, vcc
	v_cmp_ge_u32_e32 vcc, v18, v43
	v_addc_co_u32_e64 v44, s[0:1], 0, v44, s[0:1]
	v_cmp_ge_u32_e64 s[0:1], v19, v43
	v_addc_co_u32_e64 v44, s[2:3], 0, v44, s[2:3]
	v_cmp_ge_u32_e64 s[2:3], v20, v43
	v_addc_co_u32_e64 v44, vcc, 0, v44, vcc
	v_cmp_ge_u32_e32 vcc, v21, v43
	v_addc_co_u32_e64 v44, s[0:1], 0, v44, s[0:1]
	v_cmp_ge_u32_e64 s[0:1], v22, v43
	v_addc_co_u32_e64 v44, s[2:3], 0, v44, s[2:3]
	v_cmp_ge_u32_e64 s[2:3], v23, v43
	v_addc_co_u32_e64 v44, vcc, 0, v44, vcc
	v_cmp_ge_u32_e32 vcc, v24, v43
	v_addc_co_u32_e64 v44, s[0:1], 0, v44, s[0:1]
	v_cmp_ge_u32_e64 s[0:1], v25, v43
	v_addc_co_u32_e64 v44, s[2:3], 0, v44, s[2:3]
	v_cmp_ge_u32_e64 s[2:3], v26, v43
	v_addc_co_u32_e64 v44, vcc, 0, v44, vcc
	v_cmp_ge_u32_e32 vcc, v27, v43
	v_addc_co_u32_e64 v44, s[0:1], 0, v44, s[0:1]
	v_cmp_ge_u32_e64 s[0:1], v28, v43
	v_addc_co_u32_e64 v44, s[2:3], 0, v44, s[2:3]
	v_cmp_ge_u32_e64 s[2:3], v29, v43
	v_addc_co_u32_e64 v44, vcc, 0, v44, vcc
	v_cmp_ge_u32_e32 vcc, v30, v43
	v_addc_co_u32_e64 v44, s[0:1], 0, v44, s[0:1]
	v_cmp_ge_u32_e64 s[0:1], v31, v43
	v_addc_co_u32_e64 v44, s[2:3], 0, v44, s[2:3]
	v_addc_co_u32_e64 v44, vcc, 0, v44, vcc
	v_addc_co_u32_e64 v44, s[0:1], 0, v44, s[0:1]
	v_mov_b32_e32 v45, v44
	s_nop 1
	v_add_u32_dpp v45, v45, v45 row_ror:1 row_mask:0xf bank_mask:0xf
	s_nop 1
	v_add_u32_dpp v45, v45, v45 row_ror:2 row_mask:0xf bank_mask:0xf
	s_nop 1
	v_add_u32_dpp v45, v45, v45 row_ror:4 row_mask:0xf bank_mask:0xf
	s_nop 1
	v_add_u32_dpp v45, v45, v45 row_ror:8 row_mask:0xf bank_mask:0xf
	s_nop 0
	v_cmp_le_u32_e32 vcc, 0x100, v45
	s_nop 1
	v_cndmask_b32_e32 v36, v36, v42, vcc
	v_cndmask_b32_e32 v46, v46, v45, vcc
	v_cndmask_b32_e32 v47, v47, v44, vcc
	v_or_b32_e32 v42, 8, v36
	v_lshlrev_b32_e32 v41, v39, v42
	v_add_u32_e64 v43, v34, v41 clamp
	v_mov_b32_e32 v44, 0
	v_cmp_ge_u32_e32 vcc, v0, v43
	v_cmp_ge_u32_e64 s[0:1], v1, v43
	v_cmp_ge_u32_e64 s[2:3], v2, v43
	v_addc_co_u32_e64 v44, vcc, 0, v44, vcc
	v_cmp_ge_u32_e32 vcc, v3, v43
	v_addc_co_u32_e64 v44, s[0:1], 0, v44, s[0:1]
	v_cmp_ge_u32_e64 s[0:1], v4, v43
	v_addc_co_u32_e64 v44, s[2:3], 0, v44, s[2:3]
	v_cmp_ge_u32_e64 s[2:3], v5, v43
	v_addc_co_u32_e64 v44, vcc, 0, v44, vcc
	v_cmp_ge_u32_e32 vcc, v6, v43
	v_addc_co_u32_e64 v44, s[0:1], 0, v44, s[0:1]
	v_cmp_ge_u32_e64 s[0:1], v7, v43
	v_addc_co_u32_e64 v44, s[2:3], 0, v44, s[2:3]
	v_cmp_ge_u32_e64 s[2:3], v8, v43
	v_addc_co_u32_e64 v44, vcc, 0, v44, vcc
	v_cmp_ge_u32_e32 vcc, v9, v43
	v_addc_co_u32_e64 v44, s[0:1], 0, v44, s[0:1]
	v_cmp_ge_u32_e64 s[0:1], v10, v43
	v_addc_co_u32_e64 v44, s[2:3], 0, v44, s[2:3]
	v_cmp_ge_u32_e64 s[2:3], v11, v43
	v_addc_co_u32_e64 v44, vcc, 0, v44, vcc
	v_cmp_ge_u32_e32 vcc, v12, v43
	v_addc_co_u32_e64 v44, s[0:1], 0, v44, s[0:1]
	v_cmp_ge_u32_e64 s[0:1], v13, v43
	v_addc_co_u32_e64 v44, s[2:3], 0, v44, s[2:3]
	v_cmp_ge_u32_e64 s[2:3], v14, v43
	v_addc_co_u32_e64 v44, vcc, 0, v44, vcc
	v_cmp_ge_u32_e32 vcc, v15, v43
	v_addc_co_u32_e64 v44, s[0:1], 0, v44, s[0:1]
	v_cmp_ge_u32_e64 s[0:1], v16, v43
	v_addc_co_u32_e64 v44, s[2:3], 0, v44, s[2:3]
	v_cmp_ge_u32_e64 s[2:3], v17, v43
	v_addc_co_u32_e64 v44, vcc, 0, v44, vcc
	v_cmp_ge_u32_e32 vcc, v18, v43
	v_addc_co_u32_e64 v44, s[0:1], 0, v44, s[0:1]
	v_cmp_ge_u32_e64 s[0:1], v19, v43
	v_addc_co_u32_e64 v44, s[2:3], 0, v44, s[2:3]
	v_cmp_ge_u32_e64 s[2:3], v20, v43
	v_addc_co_u32_e64 v44, vcc, 0, v44, vcc
	v_cmp_ge_u32_e32 vcc, v21, v43
	v_addc_co_u32_e64 v44, s[0:1], 0, v44, s[0:1]
	v_cmp_ge_u32_e64 s[0:1], v22, v43
	v_addc_co_u32_e64 v44, s[2:3], 0, v44, s[2:3]
	v_cmp_ge_u32_e64 s[2:3], v23, v43
	v_addc_co_u32_e64 v44, vcc, 0, v44, vcc
	v_cmp_ge_u32_e32 vcc, v24, v43
	v_addc_co_u32_e64 v44, s[0:1], 0, v44, s[0:1]
	v_cmp_ge_u32_e64 s[0:1], v25, v43
	v_addc_co_u32_e64 v44, s[2:3], 0, v44, s[2:3]
	v_cmp_ge_u32_e64 s[2:3], v26, v43
	v_addc_co_u32_e64 v44, vcc, 0, v44, vcc
	v_cmp_ge_u32_e32 vcc, v27, v43
	v_addc_co_u32_e64 v44, s[0:1], 0, v44, s[0:1]
	v_cmp_ge_u32_e64 s[0:1], v28, v43
	v_addc_co_u32_e64 v44, s[2:3], 0, v44, s[2:3]
	v_cmp_ge_u32_e64 s[2:3], v29, v43
	v_addc_co_u32_e64 v44, vcc, 0, v44, vcc
	v_cmp_ge_u32_e32 vcc, v30, v43
	v_addc_co_u32_e64 v44, s[0:1], 0, v44, s[0:1]
	v_cmp_ge_u32_e64 s[0:1], v31, v43
	v_addc_co_u32_e64 v44, s[2:3], 0, v44, s[2:3]
	v_addc_co_u32_e64 v44, vcc, 0, v44, vcc
	v_addc_co_u32_e64 v44, s[0:1], 0, v44, s[0:1]
	v_mov_b32_e32 v45, v44
	s_nop 1
	v_add_u32_dpp v45, v45, v45 row_ror:1 row_mask:0xf bank_mask:0xf
	s_nop 1
	v_add_u32_dpp v45, v45, v45 row_ror:2 row_mask:0xf bank_mask:0xf
	s_nop 1
	v_add_u32_dpp v45, v45, v45 row_ror:4 row_mask:0xf bank_mask:0xf
	s_nop 1
	v_add_u32_dpp v45, v45, v45 row_ror:8 row_mask:0xf bank_mask:0xf
	s_nop 0
	v_cmp_le_u32_e32 vcc, 0x100, v45
	s_nop 1
	v_cndmask_b32_e32 v36, v36, v42, vcc
	v_cndmask_b32_e32 v46, v46, v45, vcc
	v_cndmask_b32_e32 v47, v47, v44, vcc
	v_or_b32_e32 v42, 4, v36
	v_lshlrev_b32_e32 v41, v39, v42
	v_add_u32_e64 v43, v34, v41 clamp
	v_mov_b32_e32 v44, 0
	v_cmp_ge_u32_e32 vcc, v0, v43
	v_cmp_ge_u32_e64 s[0:1], v1, v43
	v_cmp_ge_u32_e64 s[2:3], v2, v43
	v_addc_co_u32_e64 v44, vcc, 0, v44, vcc
	v_cmp_ge_u32_e32 vcc, v3, v43
	v_addc_co_u32_e64 v44, s[0:1], 0, v44, s[0:1]
	v_cmp_ge_u32_e64 s[0:1], v4, v43
	v_addc_co_u32_e64 v44, s[2:3], 0, v44, s[2:3]
	v_cmp_ge_u32_e64 s[2:3], v5, v43
	v_addc_co_u32_e64 v44, vcc, 0, v44, vcc
	v_cmp_ge_u32_e32 vcc, v6, v43
	v_addc_co_u32_e64 v44, s[0:1], 0, v44, s[0:1]
	v_cmp_ge_u32_e64 s[0:1], v7, v43
	v_addc_co_u32_e64 v44, s[2:3], 0, v44, s[2:3]
	v_cmp_ge_u32_e64 s[2:3], v8, v43
	v_addc_co_u32_e64 v44, vcc, 0, v44, vcc
	v_cmp_ge_u32_e32 vcc, v9, v43
	v_addc_co_u32_e64 v44, s[0:1], 0, v44, s[0:1]
	v_cmp_ge_u32_e64 s[0:1], v10, v43
	v_addc_co_u32_e64 v44, s[2:3], 0, v44, s[2:3]
	v_cmp_ge_u32_e64 s[2:3], v11, v43
	v_addc_co_u32_e64 v44, vcc, 0, v44, vcc
	v_cmp_ge_u32_e32 vcc, v12, v43
	v_addc_co_u32_e64 v44, s[0:1], 0, v44, s[0:1]
	v_cmp_ge_u32_e64 s[0:1], v13, v43
	v_addc_co_u32_e64 v44, s[2:3], 0, v44, s[2:3]
	v_cmp_ge_u32_e64 s[2:3], v14, v43
	v_addc_co_u32_e64 v44, vcc, 0, v44, vcc
	v_cmp_ge_u32_e32 vcc, v15, v43
	v_addc_co_u32_e64 v44, s[0:1], 0, v44, s[0:1]
	v_cmp_ge_u32_e64 s[0:1], v16, v43
	v_addc_co_u32_e64 v44, s[2:3], 0, v44, s[2:3]
	v_cmp_ge_u32_e64 s[2:3], v17, v43
	v_addc_co_u32_e64 v44, vcc, 0, v44, vcc
	v_cmp_ge_u32_e32 vcc, v18, v43
	v_addc_co_u32_e64 v44, s[0:1], 0, v44, s[0:1]
	v_cmp_ge_u32_e64 s[0:1], v19, v43
	v_addc_co_u32_e64 v44, s[2:3], 0, v44, s[2:3]
	v_cmp_ge_u32_e64 s[2:3], v20, v43
	v_addc_co_u32_e64 v44, vcc, 0, v44, vcc
	v_cmp_ge_u32_e32 vcc, v21, v43
	v_addc_co_u32_e64 v44, s[0:1], 0, v44, s[0:1]
	v_cmp_ge_u32_e64 s[0:1], v22, v43
	v_addc_co_u32_e64 v44, s[2:3], 0, v44, s[2:3]
	v_cmp_ge_u32_e64 s[2:3], v23, v43
	v_addc_co_u32_e64 v44, vcc, 0, v44, vcc
	v_cmp_ge_u32_e32 vcc, v24, v43
	v_addc_co_u32_e64 v44, s[0:1], 0, v44, s[0:1]
	v_cmp_ge_u32_e64 s[0:1], v25, v43
	v_addc_co_u32_e64 v44, s[2:3], 0, v44, s[2:3]
	v_cmp_ge_u32_e64 s[2:3], v26, v43
	v_addc_co_u32_e64 v44, vcc, 0, v44, vcc
	v_cmp_ge_u32_e32 vcc, v27, v43
	v_addc_co_u32_e64 v44, s[0:1], 0, v44, s[0:1]
	v_cmp_ge_u32_e64 s[0:1], v28, v43
	v_addc_co_u32_e64 v44, s[2:3], 0, v44, s[2:3]
	v_cmp_ge_u32_e64 s[2:3], v29, v43
	v_addc_co_u32_e64 v44, vcc, 0, v44, vcc
	v_cmp_ge_u32_e32 vcc, v30, v43
	v_addc_co_u32_e64 v44, s[0:1], 0, v44, s[0:1]
	v_cmp_ge_u32_e64 s[0:1], v31, v43
	v_addc_co_u32_e64 v44, s[2:3], 0, v44, s[2:3]
	v_addc_co_u32_e64 v44, vcc, 0, v44, vcc
	v_addc_co_u32_e64 v44, s[0:1], 0, v44, s[0:1]
	v_mov_b32_e32 v45, v44
	s_nop 1
	v_add_u32_dpp v45, v45, v45 row_ror:1 row_mask:0xf bank_mask:0xf
	s_nop 1
	v_add_u32_dpp v45, v45, v45 row_ror:2 row_mask:0xf bank_mask:0xf
	s_nop 1
	v_add_u32_dpp v45, v45, v45 row_ror:4 row_mask:0xf bank_mask:0xf
	s_nop 1
	v_add_u32_dpp v45, v45, v45 row_ror:8 row_mask:0xf bank_mask:0xf
	s_nop 0
	v_cmp_le_u32_e32 vcc, 0x100, v45
	s_nop 1
	v_cndmask_b32_e32 v36, v36, v42, vcc
	v_cndmask_b32_e32 v46, v46, v45, vcc
	v_cndmask_b32_e32 v47, v47, v44, vcc
	v_or_b32_e32 v42, 2, v36
	v_lshlrev_b32_e32 v41, v39, v42
	v_add_u32_e64 v43, v34, v41 clamp
	v_mov_b32_e32 v44, 0
	v_cmp_ge_u32_e32 vcc, v0, v43
	v_cmp_ge_u32_e64 s[0:1], v1, v43
	v_cmp_ge_u32_e64 s[2:3], v2, v43
	v_addc_co_u32_e64 v44, vcc, 0, v44, vcc
	v_cmp_ge_u32_e32 vcc, v3, v43
	v_addc_co_u32_e64 v44, s[0:1], 0, v44, s[0:1]
	v_cmp_ge_u32_e64 s[0:1], v4, v43
	v_addc_co_u32_e64 v44, s[2:3], 0, v44, s[2:3]
	v_cmp_ge_u32_e64 s[2:3], v5, v43
	v_addc_co_u32_e64 v44, vcc, 0, v44, vcc
	v_cmp_ge_u32_e32 vcc, v6, v43
	v_addc_co_u32_e64 v44, s[0:1], 0, v44, s[0:1]
	v_cmp_ge_u32_e64 s[0:1], v7, v43
	v_addc_co_u32_e64 v44, s[2:3], 0, v44, s[2:3]
	v_cmp_ge_u32_e64 s[2:3], v8, v43
	v_addc_co_u32_e64 v44, vcc, 0, v44, vcc
	v_cmp_ge_u32_e32 vcc, v9, v43
	v_addc_co_u32_e64 v44, s[0:1], 0, v44, s[0:1]
	v_cmp_ge_u32_e64 s[0:1], v10, v43
	v_addc_co_u32_e64 v44, s[2:3], 0, v44, s[2:3]
	v_cmp_ge_u32_e64 s[2:3], v11, v43
	v_addc_co_u32_e64 v44, vcc, 0, v44, vcc
	v_cmp_ge_u32_e32 vcc, v12, v43
	v_addc_co_u32_e64 v44, s[0:1], 0, v44, s[0:1]
	v_cmp_ge_u32_e64 s[0:1], v13, v43
	v_addc_co_u32_e64 v44, s[2:3], 0, v44, s[2:3]
	v_cmp_ge_u32_e64 s[2:3], v14, v43
	v_addc_co_u32_e64 v44, vcc, 0, v44, vcc
	v_cmp_ge_u32_e32 vcc, v15, v43
	v_addc_co_u32_e64 v44, s[0:1], 0, v44, s[0:1]
	v_cmp_ge_u32_e64 s[0:1], v16, v43
	v_addc_co_u32_e64 v44, s[2:3], 0, v44, s[2:3]
	v_cmp_ge_u32_e64 s[2:3], v17, v43
	v_addc_co_u32_e64 v44, vcc, 0, v44, vcc
	v_cmp_ge_u32_e32 vcc, v18, v43
	v_addc_co_u32_e64 v44, s[0:1], 0, v44, s[0:1]
	v_cmp_ge_u32_e64 s[0:1], v19, v43
	v_addc_co_u32_e64 v44, s[2:3], 0, v44, s[2:3]
	v_cmp_ge_u32_e64 s[2:3], v20, v43
	v_addc_co_u32_e64 v44, vcc, 0, v44, vcc
	v_cmp_ge_u32_e32 vcc, v21, v43
	v_addc_co_u32_e64 v44, s[0:1], 0, v44, s[0:1]
	v_cmp_ge_u32_e64 s[0:1], v22, v43
	v_addc_co_u32_e64 v44, s[2:3], 0, v44, s[2:3]
	v_cmp_ge_u32_e64 s[2:3], v23, v43
	v_addc_co_u32_e64 v44, vcc, 0, v44, vcc
	v_cmp_ge_u32_e32 vcc, v24, v43
	v_addc_co_u32_e64 v44, s[0:1], 0, v44, s[0:1]
	v_cmp_ge_u32_e64 s[0:1], v25, v43
	v_addc_co_u32_e64 v44, s[2:3], 0, v44, s[2:3]
	v_cmp_ge_u32_e64 s[2:3], v26, v43
	v_addc_co_u32_e64 v44, vcc, 0, v44, vcc
	v_cmp_ge_u32_e32 vcc, v27, v43
	v_addc_co_u32_e64 v44, s[0:1], 0, v44, s[0:1]
	v_cmp_ge_u32_e64 s[0:1], v28, v43
	v_addc_co_u32_e64 v44, s[2:3], 0, v44, s[2:3]
	v_cmp_ge_u32_e64 s[2:3], v29, v43
	v_addc_co_u32_e64 v44, vcc, 0, v44, vcc
	v_cmp_ge_u32_e32 vcc, v30, v43
	v_addc_co_u32_e64 v44, s[0:1], 0, v44, s[0:1]
	v_cmp_ge_u32_e64 s[0:1], v31, v43
	v_addc_co_u32_e64 v44, s[2:3], 0, v44, s[2:3]
	v_addc_co_u32_e64 v44, vcc, 0, v44, vcc
	v_addc_co_u32_e64 v44, s[0:1], 0, v44, s[0:1]
	v_mov_b32_e32 v45, v44
	s_nop 1
	v_add_u32_dpp v45, v45, v45 row_ror:1 row_mask:0xf bank_mask:0xf
	s_nop 1
	v_add_u32_dpp v45, v45, v45 row_ror:2 row_mask:0xf bank_mask:0xf
	s_nop 1
	v_add_u32_dpp v45, v45, v45 row_ror:4 row_mask:0xf bank_mask:0xf
	s_nop 1
	v_add_u32_dpp v45, v45, v45 row_ror:8 row_mask:0xf bank_mask:0xf
	s_nop 0
	v_cmp_le_u32_e32 vcc, 0x100, v45
	s_nop 1
	v_cndmask_b32_e32 v36, v36, v42, vcc
	v_cndmask_b32_e32 v46, v46, v45, vcc
	v_cndmask_b32_e32 v47, v47, v44, vcc
	v_or_b32_e32 v42, 1, v36
	v_lshlrev_b32_e32 v41, v39, v42
	v_add_u32_e64 v43, v34, v41 clamp
	v_mov_b32_e32 v44, 0
	v_cmp_ge_u32_e32 vcc, v0, v43
	v_cmp_ge_u32_e64 s[0:1], v1, v43
	v_cmp_ge_u32_e64 s[2:3], v2, v43
	v_addc_co_u32_e64 v44, vcc, 0, v44, vcc
	v_cmp_ge_u32_e32 vcc, v3, v43
	v_addc_co_u32_e64 v44, s[0:1], 0, v44, s[0:1]
	v_cmp_ge_u32_e64 s[0:1], v4, v43
	v_addc_co_u32_e64 v44, s[2:3], 0, v44, s[2:3]
	v_cmp_ge_u32_e64 s[2:3], v5, v43
	v_addc_co_u32_e64 v44, vcc, 0, v44, vcc
	v_cmp_ge_u32_e32 vcc, v6, v43
	v_addc_co_u32_e64 v44, s[0:1], 0, v44, s[0:1]
	v_cmp_ge_u32_e64 s[0:1], v7, v43
	v_addc_co_u32_e64 v44, s[2:3], 0, v44, s[2:3]
	v_cmp_ge_u32_e64 s[2:3], v8, v43
	v_addc_co_u32_e64 v44, vcc, 0, v44, vcc
	v_cmp_ge_u32_e32 vcc, v9, v43
	v_addc_co_u32_e64 v44, s[0:1], 0, v44, s[0:1]
	v_cmp_ge_u32_e64 s[0:1], v10, v43
	v_addc_co_u32_e64 v44, s[2:3], 0, v44, s[2:3]
	v_cmp_ge_u32_e64 s[2:3], v11, v43
	v_addc_co_u32_e64 v44, vcc, 0, v44, vcc
	v_cmp_ge_u32_e32 vcc, v12, v43
	v_addc_co_u32_e64 v44, s[0:1], 0, v44, s[0:1]
	v_cmp_ge_u32_e64 s[0:1], v13, v43
	v_addc_co_u32_e64 v44, s[2:3], 0, v44, s[2:3]
	v_cmp_ge_u32_e64 s[2:3], v14, v43
	v_addc_co_u32_e64 v44, vcc, 0, v44, vcc
	v_cmp_ge_u32_e32 vcc, v15, v43
	v_addc_co_u32_e64 v44, s[0:1], 0, v44, s[0:1]
	v_cmp_ge_u32_e64 s[0:1], v16, v43
	v_addc_co_u32_e64 v44, s[2:3], 0, v44, s[2:3]
	v_cmp_ge_u32_e64 s[2:3], v17, v43
	v_addc_co_u32_e64 v44, vcc, 0, v44, vcc
	v_cmp_ge_u32_e32 vcc, v18, v43
	v_addc_co_u32_e64 v44, s[0:1], 0, v44, s[0:1]
	v_cmp_ge_u32_e64 s[0:1], v19, v43
	v_addc_co_u32_e64 v44, s[2:3], 0, v44, s[2:3]
	v_cmp_ge_u32_e64 s[2:3], v20, v43
	v_addc_co_u32_e64 v44, vcc, 0, v44, vcc
	v_cmp_ge_u32_e32 vcc, v21, v43
	v_addc_co_u32_e64 v44, s[0:1], 0, v44, s[0:1]
	v_cmp_ge_u32_e64 s[0:1], v22, v43
	v_addc_co_u32_e64 v44, s[2:3], 0, v44, s[2:3]
	v_cmp_ge_u32_e64 s[2:3], v23, v43
	v_addc_co_u32_e64 v44, vcc, 0, v44, vcc
	v_cmp_ge_u32_e32 vcc, v24, v43
	v_addc_co_u32_e64 v44, s[0:1], 0, v44, s[0:1]
	v_cmp_ge_u32_e64 s[0:1], v25, v43
	v_addc_co_u32_e64 v44, s[2:3], 0, v44, s[2:3]
	v_cmp_ge_u32_e64 s[2:3], v26, v43
	v_addc_co_u32_e64 v44, vcc, 0, v44, vcc
	v_cmp_ge_u32_e32 vcc, v27, v43
	v_addc_co_u32_e64 v44, s[0:1], 0, v44, s[0:1]
	v_cmp_ge_u32_e64 s[0:1], v28, v43
	v_addc_co_u32_e64 v44, s[2:3], 0, v44, s[2:3]
	v_cmp_ge_u32_e64 s[2:3], v29, v43
	v_addc_co_u32_e64 v44, vcc, 0, v44, vcc
	v_cmp_ge_u32_e32 vcc, v30, v43
	v_addc_co_u32_e64 v44, s[0:1], 0, v44, s[0:1]
	v_cmp_ge_u32_e64 s[0:1], v31, v43
	v_addc_co_u32_e64 v44, s[2:3], 0, v44, s[2:3]
	v_addc_co_u32_e64 v44, vcc, 0, v44, vcc
	v_addc_co_u32_e64 v44, s[0:1], 0, v44, s[0:1]
	v_mov_b32_e32 v45, v44
	s_nop 1
	v_add_u32_dpp v45, v45, v45 row_ror:1 row_mask:0xf bank_mask:0xf
	s_nop 1
	v_add_u32_dpp v45, v45, v45 row_ror:2 row_mask:0xf bank_mask:0xf
	s_nop 1
	v_add_u32_dpp v45, v45, v45 row_ror:4 row_mask:0xf bank_mask:0xf
	s_nop 1
	v_add_u32_dpp v45, v45, v45 row_ror:8 row_mask:0xf bank_mask:0xf
	s_nop 0
	v_cmp_le_u32_e32 vcc, 0x100, v45
	s_nop 1
	v_cndmask_b32_e32 v36, v36, v42, vcc
	v_cndmask_b32_e32 v46, v46, v45, vcc
	v_cndmask_b32_e32 v47, v47, v44, vcc
	v_lshlrev_b32_e32 v41, v39, v36
	v_add_u32_e32 v41, v34, v41
	v_cmp_ge_u32_e32 vcc, 0x140, v46
	v_cmp_eq_u32_e64 s[0:1], 0, v39
	v_lshlrev_b32_e32 v42, v39, v200
	v_add_u32_e32 v42, -1, v42
	s_or_b64 vcc, vcc, s[0:1]
	s_andn2_b64 s[0:1], vcc, s[50:51]
	s_nor_b64 s[2:3], vcc, s[50:51]
	s_or_b64 s[50:51], s[50:51], vcc
	v_add_u32_e64 v42, v41, v42 clamp
	v_min_u32_e32 v42, v42, v35
	v_cndmask_b32_e64 v37, v37, v41, s[0:1]
	v_cndmask_b32_e64 v62, v62, v47, s[0:1]
	v_cndmask_b32_e64 v35, v35, v42, s[2:3]
	v_cndmask_b32_e64 v34, v34, v41, s[2:3]
	s_cmp_eq_u64 s[50:51], -1
	s_cbranch_scc0 .Lp2apr0_iter
	s_mov_b64 exec, s[22:23]
	v_mov_b32_e32 v61, v62
	s_nop 1
	v_add_u32_dpp v61, v61, v61 row_shr:1 row_mask:0xf bank_mask:0xf bound_ctrl:1
	s_nop 1
	v_add_u32_dpp v61, v61, v61 row_shr:2 row_mask:0xf bank_mask:0xf bound_ctrl:1
	s_nop 1
	v_add_u32_dpp v61, v61, v61 row_shr:4 row_mask:0xf bank_mask:0xf bound_ctrl:1
	s_nop 1
	v_add_u32_dpp v61, v61, v61 row_shr:8 row_mask:0xf bank_mask:0xf bound_ctrl:1
	v_sub_u32_e32 v62, v61, v62
	v_cmp_ge_u32_e32 vcc, v0, v37
	v_lshl_add_u32 v41, v62, 2, v59
	s_mov_b64 exec, vcc
	ds_write_b32 v41, v0
	v_add_u32_e32 v62, 1, v62
	s_mov_b64 exec, s[22:23]
	v_cmp_ge_u32_e32 vcc, v1, v37
	v_lshl_add_u32 v41, v62, 2, v59
	s_mov_b64 exec, vcc
	ds_write_b32 v41, v1
	v_add_u32_e32 v62, 1, v62
	s_mov_b64 exec, s[22:23]
	v_cmp_ge_u32_e32 vcc, v2, v37
	v_lshl_add_u32 v41, v62, 2, v59
	s_mov_b64 exec, vcc
	ds_write_b32 v41, v2
	v_add_u32_e32 v62, 1, v62
	s_mov_b64 exec, s[22:23]
	v_cmp_ge_u32_e32 vcc, v3, v37
	v_lshl_add_u32 v41, v62, 2, v59
	s_mov_b64 exec, vcc
	ds_write_b32 v41, v3
	v_add_u32_e32 v62, 1, v62
	s_mov_b64 exec, s[22:23]
	v_cmp_ge_u32_e32 vcc, v4, v37
	v_lshl_add_u32 v41, v62, 2, v59
	s_mov_b64 exec, vcc
	ds_write_b32 v41, v4
	v_add_u32_e32 v62, 1, v62
	s_mov_b64 exec, s[22:23]
	v_cmp_ge_u32_e32 vcc, v5, v37
	v_lshl_add_u32 v41, v62, 2, v59
	s_mov_b64 exec, vcc
	ds_write_b32 v41, v5
	v_add_u32_e32 v62, 1, v62
	s_mov_b64 exec, s[22:23]
	v_cmp_ge_u32_e32 vcc, v6, v37
	v_lshl_add_u32 v41, v62, 2, v59
	s_mov_b64 exec, vcc
	ds_write_b32 v41, v6
	v_add_u32_e32 v62, 1, v62
	s_mov_b64 exec, s[22:23]
	v_cmp_ge_u32_e32 vcc, v7, v37
	v_lshl_add_u32 v41, v62, 2, v59
	s_mov_b64 exec, vcc
	ds_write_b32 v41, v7
	v_add_u32_e32 v62, 1, v62
	s_mov_b64 exec, s[22:23]
	v_cmp_ge_u32_e32 vcc, v8, v37
	v_lshl_add_u32 v41, v62, 2, v59
	s_mov_b64 exec, vcc
	ds_write_b32 v41, v8
	v_add_u32_e32 v62, 1, v62
	s_mov_b64 exec, s[22:23]
	v_cmp_ge_u32_e32 vcc, v9, v37
	v_lshl_add_u32 v41, v62, 2, v59
	s_mov_b64 exec, vcc
	ds_write_b32 v41, v9
	v_add_u32_e32 v62, 1, v62
	s_mov_b64 exec, s[22:23]
	v_cmp_ge_u32_e32 vcc, v10, v37
	v_lshl_add_u32 v41, v62, 2, v59
	s_mov_b64 exec, vcc
	ds_write_b32 v41, v10
	v_add_u32_e32 v62, 1, v62
	s_mov_b64 exec, s[22:23]
	v_cmp_ge_u32_e32 vcc, v11, v37
	v_lshl_add_u32 v41, v62, 2, v59
	s_mov_b64 exec, vcc
	ds_write_b32 v41, v11
	v_add_u32_e32 v62, 1, v62
	s_mov_b64 exec, s[22:23]
	v_cmp_ge_u32_e32 vcc, v12, v37
	v_lshl_add_u32 v41, v62, 2, v59
	s_mov_b64 exec, vcc
	ds_write_b32 v41, v12
	v_add_u32_e32 v62, 1, v62
	s_mov_b64 exec, s[22:23]
	v_cmp_ge_u32_e32 vcc, v13, v37
	v_lshl_add_u32 v41, v62, 2, v59
	s_mov_b64 exec, vcc
	ds_write_b32 v41, v13
	v_add_u32_e32 v62, 1, v62
	s_mov_b64 exec, s[22:23]
	v_cmp_ge_u32_e32 vcc, v14, v37
	v_lshl_add_u32 v41, v62, 2, v59
	s_mov_b64 exec, vcc
	ds_write_b32 v41, v14
	v_add_u32_e32 v62, 1, v62
	s_mov_b64 exec, s[22:23]
	v_cmp_ge_u32_e32 vcc, v15, v37
	v_lshl_add_u32 v41, v62, 2, v59
	s_mov_b64 exec, vcc
	ds_write_b32 v41, v15
	v_add_u32_e32 v62, 1, v62
	s_mov_b64 exec, s[22:23]
	v_cmp_ge_u32_e32 vcc, v16, v37
	v_lshl_add_u32 v41, v62, 2, v59
	s_mov_b64 exec, vcc
	ds_write_b32 v41, v16
	v_add_u32_e32 v62, 1, v62
	s_mov_b64 exec, s[22:23]
	v_cmp_ge_u32_e32 vcc, v17, v37
	v_lshl_add_u32 v41, v62, 2, v59
	s_mov_b64 exec, vcc
	ds_write_b32 v41, v17
	v_add_u32_e32 v62, 1, v62
	s_mov_b64 exec, s[22:23]
	v_cmp_ge_u32_e32 vcc, v18, v37
	v_lshl_add_u32 v41, v62, 2, v59
	s_mov_b64 exec, vcc
	ds_write_b32 v41, v18
	v_add_u32_e32 v62, 1, v62
	s_mov_b64 exec, s[22:23]
	v_cmp_ge_u32_e32 vcc, v19, v37
	v_lshl_add_u32 v41, v62, 2, v59
	s_mov_b64 exec, vcc
	ds_write_b32 v41, v19
	v_add_u32_e32 v62, 1, v62
	s_mov_b64 exec, s[22:23]
	v_cmp_ge_u32_e32 vcc, v20, v37
	v_lshl_add_u32 v41, v62, 2, v59
	s_mov_b64 exec, vcc
	ds_write_b32 v41, v20
	v_add_u32_e32 v62, 1, v62
	s_mov_b64 exec, s[22:23]
	v_cmp_ge_u32_e32 vcc, v21, v37
	v_lshl_add_u32 v41, v62, 2, v59
	s_mov_b64 exec, vcc
	ds_write_b32 v41, v21
	v_add_u32_e32 v62, 1, v62
	s_mov_b64 exec, s[22:23]
	v_cmp_ge_u32_e32 vcc, v22, v37
	v_lshl_add_u32 v41, v62, 2, v59
	s_mov_b64 exec, vcc
	ds_write_b32 v41, v22
	v_add_u32_e32 v62, 1, v62
	s_mov_b64 exec, s[22:23]
	v_cmp_ge_u32_e32 vcc, v23, v37
	v_lshl_add_u32 v41, v62, 2, v59
	s_mov_b64 exec, vcc
	ds_write_b32 v41, v23
	v_add_u32_e32 v62, 1, v62
	s_mov_b64 exec, s[22:23]
	v_cmp_ge_u32_e32 vcc, v24, v37
	v_lshl_add_u32 v41, v62, 2, v59
	s_mov_b64 exec, vcc
	ds_write_b32 v41, v24
	v_add_u32_e32 v62, 1, v62
	s_mov_b64 exec, s[22:23]
	v_cmp_ge_u32_e32 vcc, v25, v37
	v_lshl_add_u32 v41, v62, 2, v59
	s_mov_b64 exec, vcc
	ds_write_b32 v41, v25
	v_add_u32_e32 v62, 1, v62
	s_mov_b64 exec, s[22:23]
	v_cmp_ge_u32_e32 vcc, v26, v37
	v_lshl_add_u32 v41, v62, 2, v59
	s_mov_b64 exec, vcc
	ds_write_b32 v41, v26
	v_add_u32_e32 v62, 1, v62
	s_mov_b64 exec, s[22:23]
	v_cmp_ge_u32_e32 vcc, v27, v37
	v_lshl_add_u32 v41, v62, 2, v59
	s_mov_b64 exec, vcc
	ds_write_b32 v41, v27
	v_add_u32_e32 v62, 1, v62
	s_mov_b64 exec, s[22:23]
	v_cmp_ge_u32_e32 vcc, v28, v37
	v_lshl_add_u32 v41, v62, 2, v59
	s_mov_b64 exec, vcc
	ds_write_b32 v41, v28
	v_add_u32_e32 v62, 1, v62
	s_mov_b64 exec, s[22:23]
	v_cmp_ge_u32_e32 vcc, v29, v37
	v_lshl_add_u32 v41, v62, 2, v59
	s_mov_b64 exec, vcc
	ds_write_b32 v41, v29
	v_add_u32_e32 v62, 1, v62
	s_mov_b64 exec, s[22:23]
	v_cmp_ge_u32_e32 vcc, v30, v37
	v_lshl_add_u32 v41, v62, 2, v59
	s_mov_b64 exec, vcc
	ds_write_b32 v41, v30
	v_add_u32_e32 v62, 1, v62
	s_mov_b64 exec, s[22:23]
	v_cmp_ge_u32_e32 vcc, v31, v37
	v_lshl_add_u32 v41, v62, 2, v59
	s_mov_b64 exec, vcc
	ds_write_b32 v41, v31
	v_add_u32_e32 v62, 1, v62
	s_mov_b64 exec, s[22:23]
	s_mov_b64 exec, -1
	v_and_b32_e32 v41, 0xffffe000, v37
	v_ashrrev_i32_e32 v42, 31, v41
	v_not_b32_e32 v42, v42
	v_or_b32_e32 v42, 0x80000000, v42
	v_xor_b32_e32 v63, v41, v42
	s_cmpk_lt_i32 s78, 0x141
	s_cbranch_scc1 .Lp2apr0_o0
	v_readlane_b32 s0, v63, 0
	v_readlane_b32 s73, v37, 0
	v_readlane_b32 s78, v61, 15
	v_mov_b32_e32 v231, s0
.Lp2apr0_o0:
	s_cmpk_lt_i32 s61, 0x141
	s_cbranch_scc1 .Lp2apr0_o1
	v_readlane_b32 s0, v63, 16
	v_readlane_b32 s72, v37, 16
	v_readlane_b32 s61, v61, 31
	v_mov_b32_e32 v229, s0
.Lp2apr0_o1:
	s_cmpk_lt_i32 s16, 0x141
	s_cbranch_scc1 .Lp2apr0_o2
	v_readlane_b32 s0, v63, 32
	v_readlane_b32 s71, v37, 32
	v_readlane_b32 s16, v61, 47
	v_mov_b32_e32 v230, s0
.Lp2apr0_o2:
	s_cmpk_lt_i32 s15, 0x141
	s_cbranch_scc1 .Lp2apr0_o3
	v_readlane_b32 s0, v63, 48
	v_readlane_b32 s70, v37, 48
	v_readlane_b32 s15, v61, 63
	v_mov_b32_e32 v232, s0
.Lp2apr0_o3:
.Lp2apr0_end:
	v_add_u32_e32 v59, 0x2000, v59
	v_add_u32_e32 v60, 0x2000, v60
	s_mov_b32 s22, 0
	s_mov_b32 s23, 0
	s_cmpk_gt_i32 s8, 0x140
	s_cselect_b32 s0, 0xffff, 0
	s_or_b32 s22, s22, s0
	s_cmpk_gt_i32 s14, 0x140
	s_cselect_b32 s0, 0xffff0000, 0
	s_or_b32 s22, s22, s0
	s_cmpk_gt_i32 s13, 0x140
	s_cselect_b32 s0, 0xffff, 0
	s_or_b32 s23, s23, s0
	s_cmpk_gt_i32 s5, 0x140
	s_cselect_b32 s0, 0xffff0000, 0
	s_or_b32 s23, s23, s0
	s_cmp_eq_u64 s[22:23], 0
	s_cbranch_scc1 .Lp2apr1_end
	v_mov_b32_e32 v32, s8
	v_mov_b32_e32 v41, s14
	v_mov_b32_e32 v42, s13
	v_mov_b32_e32 v43, s5
	s_nop 0
	v_mov_b32_dpp v32, v41 quad_perm:[0,1,2,3] row_mask:0x2 bank_mask:0xf
	v_mov_b32_dpp v32, v42 quad_perm:[0,1,2,3] row_mask:0x4 bank_mask:0xf
	v_mov_b32_dpp v32, v43 quad_perm:[0,1,2,3] row_mask:0x8 bank_mask:0xf
	v_mov_b32_e32 v33, s74
	v_mov_b32_e32 v41, s75
	v_mov_b32_e32 v42, s76
	v_mov_b32_e32 v43, s77
	s_nop 0
	v_mov_b32_dpp v33, v41 quad_perm:[0,1,2,3] row_mask:0x2 bank_mask:0xf
	v_mov_b32_dpp v33, v42 quad_perm:[0,1,2,3] row_mask:0x4 bank_mask:0xf
	v_mov_b32_dpp v33, v43 quad_perm:[0,1,2,3] row_mask:0x8 bank_mask:0xf
	ds_read_b128 v[0:3], v60
	ds_read_b128 v[4:7], v60 offset:256
	ds_read_b128 v[8:11], v60 offset:512
	ds_read_b128 v[12:15], v60 offset:768
	ds_read_b128 v[16:19], v60 offset:1024
	ds_read_b128 v[20:23], v60 offset:1280
	ds_read_b128 v[24:27], v60 offset:1536
	ds_read_b128 v[28:31], v60 offset:1792
	v_lshlrev_b32_e32 v41, 2, v58
	v_sub_u32_e32 v41, v32, v41
	s_waitcnt lgkmcnt(0)
	v_mov_b32_e32 v47, 20
	v_subrev_u32_e32 v42, 320, v41
	v_med3_i32 v43, v42, 0, 4
	v_add_u32_e32 v47, v47, v43
	v_cmp_lt_i32_e32 vcc, 0, v42
	v_cmp_lt_i32_e64 s[0:1], 1, v42
	v_cmp_lt_i32_e64 s[2:3], 2, v42
	v_cndmask_b32_e32 v20, 0, v20, vcc
	v_cmp_lt_i32_e32 vcc, 3, v42
	v_cndmask_b32_e64 v21, 0, v21, s[0:1]
	v_cndmask_b32_e64 v22, 0, v22, s[2:3]
	v_cndmask_b32_e32 v23, 0, v23, vcc
	v_subrev_u32_e32 v42, 384, v41
	v_med3_i32 v43, v42, 0, 4
	v_add_u32_e32 v47, v47, v43
	v_cmp_lt_i32_e32 vcc, 0, v42
	v_cmp_lt_i32_e64 s[0:1], 1, v42
	v_cmp_lt_i32_e64 s[2:3], 2, v42
	v_cndmask_b32_e32 v24, 0, v24, vcc
	v_cmp_lt_i32_e32 vcc, 3, v42
	v_cndmask_b32_e64 v25, 0, v25, s[0:1]
	v_cndmask_b32_e64 v26, 0, v26, s[2:3]
	v_cndmask_b32_e32 v27, 0, v27, vcc
	v_subrev_u32_e32 v42, 448, v41
	v_med3_i32 v43, v42, 0, 4
	v_add_u32_e32 v47, v47, v43
	v_cmp_lt_i32_e32 vcc, 0, v42
	v_cmp_lt_i32_e64 s[0:1], 1, v42
	v_cmp_lt_i32_e64 s[2:3], 2, v42
	v_cndmask_b32_e32 v28, 0, v28, vcc
	v_cmp_lt_i32_e32 vcc, 3, v42
	v_cndmask_b32_e64 v29, 0, v29, s[0:1]
	v_cndmask_b32_e64 v30, 0, v30, s[2:3]
	v_cndmask_b32_e32 v31, 0, v31, vcc
	v_max3_u32 v35, v0, v1, v2
	v_max3_u32 v35, v3, v4, v35
	v_max3_u32 v35, v5, v6, v35
	v_max3_u32 v35, v7, v8, v35
	v_max3_u32 v35, v9, v10, v35
	v_max3_u32 v35, v11, v12, v35
	v_max3_u32 v35, v13, v14, v35
	v_max3_u32 v35, v15, v16, v35
	v_max3_u32 v35, v17, v18, v35
	v_max3_u32 v35, v19, v20, v35
	v_max3_u32 v35, v21, v22, v35
	v_max3_u32 v35, v23, v24, v35
	v_max3_u32 v35, v25, v26, v35
	v_max3_u32 v35, v27, v28, v35
	v_max3_u32 v35, v29, v30, v35
	v_max_u32_e32 v35, v31, v35
	s_nop 1
	v_max_u32_dpp v35, v35, v35 row_ror:1 row_mask:0xf bank_mask:0xf
	s_nop 1
	v_max_u32_dpp v35, v35, v35 row_ror:2 row_mask:0xf bank_mask:0xf
	s_nop 1
	v_max_u32_dpp v35, v35, v35 row_ror:4 row_mask:0xf bank_mask:0xf
	s_nop 1
	v_max_u32_dpp v35, v35, v35 row_ror:8 row_mask:0xf bank_mask:0xf
	v_and_b32_e32 v34, 0xffffe000, v33
	v_cmp_eq_u32_e32 vcc, 0, v33
	s_and_b64 vcc, vcc, s[22:23]
	s_cbranch_vccz .Lp2apr1_nomin
	v_add_u32_e32 v41, -1, v0
	v_add_u32_e32 v42, -1, v1
	v_min_u32_e32 v43, v41, v42
	v_add_u32_e32 v41, -1, v2
	v_add_u32_e32 v42, -1, v3
	v_min3_u32 v43, v41, v42, v43
	v_add_u32_e32 v41, -1, v4
	v_add_u32_e32 v42, -1, v5
	v_min3_u32 v43, v41, v42, v43
	v_add_u32_e32 v41, -1, v6
	v_add_u32_e32 v42, -1, v7
	v_min3_u32 v43, v41, v42, v43
	v_add_u32_e32 v41, -1, v8
	v_add_u32_e32 v42, -1, v9
	v_min3_u32 v43, v41, v42, v43
	v_add_u32_e32 v41, -1, v10
	v_add_u32_e32 v42, -1, v11
	v_min3_u32 v43, v41, v42, v43
	v_add_u32_e32 v41, -1, v12
	v_add_u32_e32 v42, -1, v13
	v_min3_u32 v43, v41, v42, v43
	v_add_u32_e32 v41, -1, v14
	v_add_u32_e32 v42, -1, v15
	v_min3_u32 v43, v41, v42, v43
	v_add_u32_e32 v41, -1, v16
	v_add_u32_e32 v42, -1, v17
	v_min3_u32 v43, v41, v42, v43
	v_add_u32_e32 v41, -1, v18
	v_add_u32_e32 v42, -1, v19
	v_min3_u32 v43, v41, v42, v43
	v_add_u32_e32 v41, -1, v20
	v_add_u32_e32 v42, -1, v21
	v_min3_u32 v43, v41, v42, v43
	v_add_u32_e32 v41, -1, v22
	v_add_u32_e32 v42, -1, v23
	v_min3_u32 v43, v41, v42, v43
	v_add_u32_e32 v41, -1, v24
	v_add_u32_e32 v42, -1, v25
	v_min3_u32 v43, v41, v42, v43
	v_add_u32_e32 v41, -1, v26
	v_add_u32_e32 v42, -1, v27
	v_min3_u32 v43, v41, v42, v43
	v_add_u32_e32 v41, -1, v28
	v_add_u32_e32 v42, -1, v29
	v_min3_u32 v43, v41, v42, v43
	v_add_u32_e32 v41, -1, v30
	v_add_u32_e32 v42, -1, v31
	v_min3_u32 v43, v41, v42, v43
	s_nop 1
	v_min_u32_dpp v43, v43, v43 row_ror:1 row_mask:0xf bank_mask:0xf
	s_nop 1
	v_min_u32_dpp v43, v43, v43 row_ror:2 row_mask:0xf bank_mask:0xf
	s_nop 1
	v_min_u32_dpp v43, v43, v43 row_ror:4 row_mask:0xf bank_mask:0xf
	s_nop 1
	v_min_u32_dpp v43, v43, v43 row_ror:8 row_mask:0xf bank_mask:0xf
	v_add_u32_e32 v43, 1, v43
	v_cmp_eq_u32_e32 vcc, 0, v33
	s_nop 1
	v_cndmask_b32_e32 v34, v34, v43, vcc

.Lp2apr1_iter:
	v_sub_u32_e32 v38, v35, v34
	v_or_b32_e32 v41, 1, v38
	v_ffbh_u32_e32 v41, v41
	v_sub_u32_e32 v41, 26, v41
	v_max_i32_e32 v39, 0, v41
	v_mov_b32_e32 v36, 0
	v_or_b32_e32 v42, 32, v36
	v_lshlrev_b32_e32 v41, v39, v42
	v_add_u32_e64 v43, v34, v41 clamp
	v_mov_b32_e32 v44, 0
	v_cmp_ge_u32_e32 vcc, v0, v43
	v_cmp_ge_u32_e64 s[0:1], v1, v43
	v_cmp_ge_u32_e64 s[2:3], v2, v43
	v_addc_co_u32_e64 v44, vcc, 0, v44, vcc
	v_cmp_ge_u32_e32 vcc, v3, v43
	v_addc_co_u32_e64 v44, s[0:1], 0, v44, s[0:1]
	v_cmp_ge_u32_e64 s[0:1], v4, v43
	v_addc_co_u32_e64 v44, s[2:3], 0, v44, s[2:3]
	v_cmp_ge_u32_e64 s[2:3], v5, v43
	v_addc_co_u32_e64 v44, vcc, 0, v44, vcc
	v_cmp_ge_u32_e32 vcc, v6, v43
	v_addc_co_u32_e64 v44, s[0:1], 0, v44, s[0:1]
	v_cmp_ge_u32_e64 s[0:1], v7, v43
	v_addc_co_u32_e64 v44, s[2:3], 0, v44, s[2:3]
	v_cmp_ge_u32_e64 s[2:3], v8, v43
	v_addc_co_u32_e64 v44, vcc, 0, v44, vcc
	v_cmp_ge_u32_e32 vcc, v9, v43
	v_addc_co_u32_e64 v44, s[0:1], 0, v44, s[0:1]
	v_cmp_ge_u32_e64 s[0:1], v10, v43
	v_addc_co_u32_e64 v44, s[2:3], 0, v44, s[2:3]
	v_cmp_ge_u32_e64 s[2:3], v11, v43
	v_addc_co_u32_e64 v44, vcc, 0, v44, vcc
	v_cmp_ge_u32_e32 vcc, v12, v43
	v_addc_co_u32_e64 v44, s[0:1], 0, v44, s[0:1]
	v_cmp_ge_u32_e64 s[0:1], v13, v43
	v_addc_co_u32_e64 v44, s[2:3], 0, v44, s[2:3]
	v_cmp_ge_u32_e64 s[2:3], v14, v43
	v_addc_co_u32_e64 v44, vcc, 0, v44, vcc
	v_cmp_ge_u32_e32 vcc, v15, v43
	v_addc_co_u32_e64 v44, s[0:1], 0, v44, s[0:1]
	v_cmp_ge_u32_e64 s[0:1], v16, v43
	v_addc_co_u32_e64 v44, s[2:3], 0, v44, s[2:3]
	v_cmp_ge_u32_e64 s[2:3], v17, v43
	v_addc_co_u32_e64 v44, vcc, 0, v44, vcc
	v_cmp_ge_u32_e32 vcc, v18, v43
	v_addc_co_u32_e64 v44, s[0:1], 0, v44, s[0:1]
	v_cmp_ge_u32_e64 s[0:1], v19, v43
	v_addc_co_u32_e64 v44, s[2:3], 0, v44, s[2:3]
	v_cmp_ge_u32_e64 s[2:3], v20, v43
	v_addc_co_u32_e64 v44, vcc, 0, v44, vcc
	v_cmp_ge_u32_e32 vcc, v21, v43
	v_addc_co_u32_e64 v44, s[0:1], 0, v44, s[0:1]
	v_cmp_ge_u32_e64 s[0:1], v22, v43
	v_addc_co_u32_e64 v44, s[2:3], 0, v44, s[2:3]
	v_cmp_ge_u32_e64 s[2:3], v23, v43
	v_addc_co_u32_e64 v44, vcc, 0, v44, vcc
	v_cmp_ge_u32_e32 vcc, v24, v43
	v_addc_co_u32_e64 v44, s[0:1], 0, v44, s[0:1]
	v_cmp_ge_u32_e64 s[0:1], v25, v43
	v_addc_co_u32_e64 v44, s[2:3], 0, v44, s[2:3]
	v_cmp_ge_u32_e64 s[2:3], v26, v43
	v_addc_co_u32_e64 v44, vcc, 0, v44, vcc
	v_cmp_ge_u32_e32 vcc, v27, v43
	v_addc_co_u32_e64 v44, s[0:1], 0, v44, s[0:1]
	v_cmp_ge_u32_e64 s[0:1], v28, v43
	v_addc_co_u32_e64 v44, s[2:3], 0, v44, s[2:3]
	v_cmp_ge_u32_e64 s[2:3], v29, v43
	v_addc_co_u32_e64 v44, vcc, 0, v44, vcc
	v_cmp_ge_u32_e32 vcc, v30, v43
	v_addc_co_u32_e64 v44, s[0:1], 0, v44, s[0:1]
	v_cmp_ge_u32_e64 s[0:1], v31, v43
	v_addc_co_u32_e64 v44, s[2:3], 0, v44, s[2:3]
	v_addc_co_u32_e64 v44, vcc, 0, v44, vcc
	v_addc_co_u32_e64 v44, s[0:1], 0, v44, s[0:1]
	v_mov_b32_e32 v45, v44
	s_nop 1
	v_add_u32_dpp v45, v45, v45 row_ror:1 row_mask:0xf bank_mask:0xf
	s_nop 1
	v_add_u32_dpp v45, v45, v45 row_ror:2 row_mask:0xf bank_mask:0xf
	s_nop 1
	v_add_u32_dpp v45, v45, v45 row_ror:4 row_mask:0xf bank_mask:0xf
	s_nop 1
	v_add_u32_dpp v45, v45, v45 row_ror:8 row_mask:0xf bank_mask:0xf
	s_nop 0
	v_cmp_le_u32_e32 vcc, 0x100, v45
	s_nop 1
	v_cndmask_b32_e32 v36, v36, v42, vcc
	v_cndmask_b32_e32 v46, v46, v45, vcc
	v_cndmask_b32_e32 v47, v47, v44, vcc
	v_or_b32_e32 v42, 16, v36
	v_lshlrev_b32_e32 v41, v39, v42
	v_add_u32_e64 v43, v34, v41 clamp
	v_mov_b32_e32 v44, 0
	v_cmp_ge_u32_e32 vcc, v0, v43
	v_cmp_ge_u32_e64 s[0:1], v1, v43
	v_cmp_ge_u32_e64 s[2:3], v2, v43
	v_addc_co_u32_e64 v44, vcc, 0, v44, vcc
	v_cmp_ge_u32_e32 vcc, v3, v43
	v_addc_co_u32_e64 v44, s[0:1], 0, v44, s[0:1]
	v_cmp_ge_u32_e64 s[0:1], v4, v43
	v_addc_co_u32_e64 v44, s[2:3], 0, v44, s[2:3]
	v_cmp_ge_u32_e64 s[2:3], v5, v43
	v_addc_co_u32_e64 v44, vcc, 0, v44, vcc
	v_cmp_ge_u32_e32 vcc, v6, v43
	v_addc_co_u32_e64 v44, s[0:1], 0, v44, s[0:1]
	v_cmp_ge_u32_e64 s[0:1], v7, v43
	v_addc_co_u32_e64 v44, s[2:3], 0, v44, s[2:3]
	v_cmp_ge_u32_e64 s[2:3], v8, v43
	v_addc_co_u32_e64 v44, vcc, 0, v44, vcc
	v_cmp_ge_u32_e32 vcc, v9, v43
	v_addc_co_u32_e64 v44, s[0:1], 0, v44, s[0:1]
	v_cmp_ge_u32_e64 s[0:1], v10, v43
	v_addc_co_u32_e64 v44, s[2:3], 0, v44, s[2:3]
	v_cmp_ge_u32_e64 s[2:3], v11, v43
	v_addc_co_u32_e64 v44, vcc, 0, v44, vcc
	v_cmp_ge_u32_e32 vcc, v12, v43
	v_addc_co_u32_e64 v44, s[0:1], 0, v44, s[0:1]
	v_cmp_ge_u32_e64 s[0:1], v13, v43
	v_addc_co_u32_e64 v44, s[2:3], 0, v44, s[2:3]
	v_cmp_ge_u32_e64 s[2:3], v14, v43
	v_addc_co_u32_e64 v44, vcc, 0, v44, vcc
	v_cmp_ge_u32_e32 vcc, v15, v43
	v_addc_co_u32_e64 v44, s[0:1], 0, v44, s[0:1]
	v_cmp_ge_u32_e64 s[0:1], v16, v43
	v_addc_co_u32_e64 v44, s[2:3], 0, v44, s[2:3]
	v_cmp_ge_u32_e64 s[2:3], v17, v43
	v_addc_co_u32_e64 v44, vcc, 0, v44, vcc
	v_cmp_ge_u32_e32 vcc, v18, v43
	v_addc_co_u32_e64 v44, s[0:1], 0, v44, s[0:1]
	v_cmp_ge_u32_e64 s[0:1], v19, v43
	v_addc_co_u32_e64 v44, s[2:3], 0, v44, s[2:3]
	v_cmp_ge_u32_e64 s[2:3], v20, v43
	v_addc_co_u32_e64 v44, vcc, 0, v44, vcc
	v_cmp_ge_u32_e32 vcc, v21, v43
	v_addc_co_u32_e64 v44, s[0:1], 0, v44, s[0:1]
	v_cmp_ge_u32_e64 s[0:1], v22, v43
	v_addc_co_u32_e64 v44, s[2:3], 0, v44, s[2:3]
	v_cmp_ge_u32_e64 s[2:3], v23, v43
	v_addc_co_u32_e64 v44, vcc, 0, v44, vcc
	v_cmp_ge_u32_e32 vcc, v24, v43
	v_addc_co_u32_e64 v44, s[0:1], 0, v44, s[0:1]
	v_cmp_ge_u32_e64 s[0:1], v25, v43
	v_addc_co_u32_e64 v44, s[2:3], 0, v44, s[2:3]
	v_cmp_ge_u32_e64 s[2:3], v26, v43
	v_addc_co_u32_e64 v44, vcc, 0, v44, vcc
	v_cmp_ge_u32_e32 vcc, v27, v43
	v_addc_co_u32_e64 v44, s[0:1], 0, v44, s[0:1]
	v_cmp_ge_u32_e64 s[0:1], v28, v43
	v_addc_co_u32_e64 v44, s[2:3], 0, v44, s[2:3]
	v_cmp_ge_u32_e64 s[2:3], v29, v43
	v_addc_co_u32_e64 v44, vcc, 0, v44, vcc
	v_cmp_ge_u32_e32 vcc, v30, v43
	v_addc_co_u32_e64 v44, s[0:1], 0, v44, s[0:1]
	v_cmp_ge_u32_e64 s[0:1], v31, v43
	v_addc_co_u32_e64 v44, s[2:3], 0, v44, s[2:3]
	v_addc_co_u32_e64 v44, vcc, 0, v44, vcc
	v_addc_co_u32_e64 v44, s[0:1], 0, v44, s[0:1]
	v_mov_b32_e32 v45, v44
	s_nop 1
	v_add_u32_dpp v45, v45, v45 row_ror:1 row_mask:0xf bank_mask:0xf
	s_nop 1
	v_add_u32_dpp v45, v45, v45 row_ror:2 row_mask:0xf bank_mask:0xf
	s_nop 1
	v_add_u32_dpp v45, v45, v45 row_ror:4 row_mask:0xf bank_mask:0xf
	s_nop 1
	v_add_u32_dpp v45, v45, v45 row_ror:8 row_mask:0xf bank_mask:0xf
	s_nop 0
	v_cmp_le_u32_e32 vcc, 0x100, v45
	s_nop 1
	v_cndmask_b32_e32 v36, v36, v42, vcc
	v_cndmask_b32_e32 v46, v46, v45, vcc
	v_cndmask_b32_e32 v47, v47, v44, vcc
	v_or_b32_e32 v42, 8, v36
	v_lshlrev_b32_e32 v41, v39, v42
	v_add_u32_e64 v43, v34, v41 clamp
	v_mov_b32_e32 v44, 0
	v_cmp_ge_u32_e32 vcc, v0, v43
	v_cmp_ge_u32_e64 s[0:1], v1, v43
	v_cmp_ge_u32_e64 s[2:3], v2, v43
	v_addc_co_u32_e64 v44, vcc, 0, v44, vcc
	v_cmp_ge_u32_e32 vcc, v3, v43
	v_addc_co_u32_e64 v44, s[0:1], 0, v44, s[0:1]
	v_cmp_ge_u32_e64 s[0:1], v4, v43
	v_addc_co_u32_e64 v44, s[2:3], 0, v44, s[2:3]
	v_cmp_ge_u32_e64 s[2:3], v5, v43
	v_addc_co_u32_e64 v44, vcc, 0, v44, vcc
	v_cmp_ge_u32_e32 vcc, v6, v43
	v_addc_co_u32_e64 v44, s[0:1], 0, v44, s[0:1]
	v_cmp_ge_u32_e64 s[0:1], v7, v43
	v_addc_co_u32_e64 v44, s[2:3], 0, v44, s[2:3]
	v_cmp_ge_u32_e64 s[2:3], v8, v43
	v_addc_co_u32_e64 v44, vcc, 0, v44, vcc
	v_cmp_ge_u32_e32 vcc, v9, v43
	v_addc_co_u32_e64 v44, s[0:1], 0, v44, s[0:1]
	v_cmp_ge_u32_e64 s[0:1], v10, v43
	v_addc_co_u32_e64 v44, s[2:3], 0, v44, s[2:3]
	v_cmp_ge_u32_e64 s[2:3], v11, v43
	v_addc_co_u32_e64 v44, vcc, 0, v44, vcc
	v_cmp_ge_u32_e32 vcc, v12, v43
	v_addc_co_u32_e64 v44, s[0:1], 0, v44, s[0:1]
	v_cmp_ge_u32_e64 s[0:1], v13, v43
	v_addc_co_u32_e64 v44, s[2:3], 0, v44, s[2:3]
	v_cmp_ge_u32_e64 s[2:3], v14, v43
	v_addc_co_u32_e64 v44, vcc, 0, v44, vcc
	v_cmp_ge_u32_e32 vcc, v15, v43
	v_addc_co_u32_e64 v44, s[0:1], 0, v44, s[0:1]
	v_cmp_ge_u32_e64 s[0:1], v16, v43
	v_addc_co_u32_e64 v44, s[2:3], 0, v44, s[2:3]
	v_cmp_ge_u32_e64 s[2:3], v17, v43
	v_addc_co_u32_e64 v44, vcc, 0, v44, vcc
	v_cmp_ge_u32_e32 vcc, v18, v43
	v_addc_co_u32_e64 v44, s[0:1], 0, v44, s[0:1]
	v_cmp_ge_u32_e64 s[0:1], v19, v43
	v_addc_co_u32_e64 v44, s[2:3], 0, v44, s[2:3]
	v_cmp_ge_u32_e64 s[2:3], v20, v43
	v_addc_co_u32_e64 v44, vcc, 0, v44, vcc
	v_cmp_ge_u32_e32 vcc, v21, v43
	v_addc_co_u32_e64 v44, s[0:1], 0, v44, s[0:1]
	v_cmp_ge_u32_e64 s[0:1], v22, v43
	v_addc_co_u32_e64 v44, s[2:3], 0, v44, s[2:3]
	v_cmp_ge_u32_e64 s[2:3], v23, v43
	v_addc_co_u32_e64 v44, vcc, 0, v44, vcc
	v_cmp_ge_u32_e32 vcc, v24, v43
	v_addc_co_u32_e64 v44, s[0:1], 0, v44, s[0:1]
	v_cmp_ge_u32_e64 s[0:1], v25, v43
	v_addc_co_u32_e64 v44, s[2:3], 0, v44, s[2:3]
	v_cmp_ge_u32_e64 s[2:3], v26, v43
	v_addc_co_u32_e64 v44, vcc, 0, v44, vcc
	v_cmp_ge_u32_e32 vcc, v27, v43
	v_addc_co_u32_e64 v44, s[0:1], 0, v44, s[0:1]
	v_cmp_ge_u32_e64 s[0:1], v28, v43
	v_addc_co_u32_e64 v44, s[2:3], 0, v44, s[2:3]
	v_cmp_ge_u32_e64 s[2:3], v29, v43
	v_addc_co_u32_e64 v44, vcc, 0, v44, vcc
	v_cmp_ge_u32_e32 vcc, v30, v43
	v_addc_co_u32_e64 v44, s[0:1], 0, v44, s[0:1]
	v_cmp_ge_u32_e64 s[0:1], v31, v43
	v_addc_co_u32_e64 v44, s[2:3], 0, v44, s[2:3]
	v_addc_co_u32_e64 v44, vcc, 0, v44, vcc
	v_addc_co_u32_e64 v44, s[0:1], 0, v44, s[0:1]
	v_mov_b32_e32 v45, v44
	s_nop 1
	v_add_u32_dpp v45, v45, v45 row_ror:1 row_mask:0xf bank_mask:0xf
	s_nop 1
	v_add_u32_dpp v45, v45, v45 row_ror:2 row_mask:0xf bank_mask:0xf
	s_nop 1
	v_add_u32_dpp v45, v45, v45 row_ror:4 row_mask:0xf bank_mask:0xf
	s_nop 1
	v_add_u32_dpp v45, v45, v45 row_ror:8 row_mask:0xf bank_mask:0xf
	s_nop 0
	v_cmp_le_u32_e32 vcc, 0x100, v45
	s_nop 1
	v_cndmask_b32_e32 v36, v36, v42, vcc
	v_cndmask_b32_e32 v46, v46, v45, vcc
	v_cndmask_b32_e32 v47, v47, v44, vcc
	v_or_b32_e32 v42, 4, v36
	v_lshlrev_b32_e32 v41, v39, v42
	v_add_u32_e64 v43, v34, v41 clamp
	v_mov_b32_e32 v44, 0
	v_cmp_ge_u32_e32 vcc, v0, v43
	v_cmp_ge_u32_e64 s[0:1], v1, v43
	v_cmp_ge_u32_e64 s[2:3], v2, v43
	v_addc_co_u32_e64 v44, vcc, 0, v44, vcc
	v_cmp_ge_u32_e32 vcc, v3, v43
	v_addc_co_u32_e64 v44, s[0:1], 0, v44, s[0:1]
	v_cmp_ge_u32_e64 s[0:1], v4, v43
	v_addc_co_u32_e64 v44, s[2:3], 0, v44, s[2:3]
	v_cmp_ge_u32_e64 s[2:3], v5, v43
	v_addc_co_u32_e64 v44, vcc, 0, v44, vcc
	v_cmp_ge_u32_e32 vcc, v6, v43
	v_addc_co_u32_e64 v44, s[0:1], 0, v44, s[0:1]
	v_cmp_ge_u32_e64 s[0:1], v7, v43
	v_addc_co_u32_e64 v44, s[2:3], 0, v44, s[2:3]
	v_cmp_ge_u32_e64 s[2:3], v8, v43
	v_addc_co_u32_e64 v44, vcc, 0, v44, vcc
	v_cmp_ge_u32_e32 vcc, v9, v43
	v_addc_co_u32_e64 v44, s[0:1], 0, v44, s[0:1]
	v_cmp_ge_u32_e64 s[0:1], v10, v43
	v_addc_co_u32_e64 v44, s[2:3], 0, v44, s[2:3]
	v_cmp_ge_u32_e64 s[2:3], v11, v43
	v_addc_co_u32_e64 v44, vcc, 0, v44, vcc
	v_cmp_ge_u32_e32 vcc, v12, v43
	v_addc_co_u32_e64 v44, s[0:1], 0, v44, s[0:1]
	v_cmp_ge_u32_e64 s[0:1], v13, v43
	v_addc_co_u32_e64 v44, s[2:3], 0, v44, s[2:3]
	v_cmp_ge_u32_e64 s[2:3], v14, v43
	v_addc_co_u32_e64 v44, vcc, 0, v44, vcc
	v_cmp_ge_u32_e32 vcc, v15, v43
	v_addc_co_u32_e64 v44, s[0:1], 0, v44, s[0:1]
	v_cmp_ge_u32_e64 s[0:1], v16, v43
	v_addc_co_u32_e64 v44, s[2:3], 0, v44, s[2:3]
	v_cmp_ge_u32_e64 s[2:3], v17, v43
	v_addc_co_u32_e64 v44, vcc, 0, v44, vcc
	v_cmp_ge_u32_e32 vcc, v18, v43
	v_addc_co_u32_e64 v44, s[0:1], 0, v44, s[0:1]
	v_cmp_ge_u32_e64 s[0:1], v19, v43
	v_addc_co_u32_e64 v44, s[2:3], 0, v44, s[2:3]
	v_cmp_ge_u32_e64 s[2:3], v20, v43
	v_addc_co_u32_e64 v44, vcc, 0, v44, vcc
	v_cmp_ge_u32_e32 vcc, v21, v43
	v_addc_co_u32_e64 v44, s[0:1], 0, v44, s[0:1]
	v_cmp_ge_u32_e64 s[0:1], v22, v43
	v_addc_co_u32_e64 v44, s[2:3], 0, v44, s[2:3]
	v_cmp_ge_u32_e64 s[2:3], v23, v43
	v_addc_co_u32_e64 v44, vcc, 0, v44, vcc
	v_cmp_ge_u32_e32 vcc, v24, v43
	v_addc_co_u32_e64 v44, s[0:1], 0, v44, s[0:1]
	v_cmp_ge_u32_e64 s[0:1], v25, v43
	v_addc_co_u32_e64 v44, s[2:3], 0, v44, s[2:3]
	v_cmp_ge_u32_e64 s[2:3], v26, v43
	v_addc_co_u32_e64 v44, vcc, 0, v44, vcc
	v_cmp_ge_u32_e32 vcc, v27, v43
	v_addc_co_u32_e64 v44, s[0:1], 0, v44, s[0:1]
	v_cmp_ge_u32_e64 s[0:1], v28, v43
	v_addc_co_u32_e64 v44, s[2:3], 0, v44, s[2:3]
	v_cmp_ge_u32_e64 s[2:3], v29, v43
	v_addc_co_u32_e64 v44, vcc, 0, v44, vcc
	v_cmp_ge_u32_e32 vcc, v30, v43
	v_addc_co_u32_e64 v44, s[0:1], 0, v44, s[0:1]
	v_cmp_ge_u32_e64 s[0:1], v31, v43
	v_addc_co_u32_e64 v44, s[2:3], 0, v44, s[2:3]
	v_addc_co_u32_e64 v44, vcc, 0, v44, vcc
	v_addc_co_u32_e64 v44, s[0:1], 0, v44, s[0:1]
	v_mov_b32_e32 v45, v44
	s_nop 1
	v_add_u32_dpp v45, v45, v45 row_ror:1 row_mask:0xf bank_mask:0xf
	s_nop 1
	v_add_u32_dpp v45, v45, v45 row_ror:2 row_mask:0xf bank_mask:0xf
	s_nop 1
	v_add_u32_dpp v45, v45, v45 row_ror:4 row_mask:0xf bank_mask:0xf
	s_nop 1
	v_add_u32_dpp v45, v45, v45 row_ror:8 row_mask:0xf bank_mask:0xf
	s_nop 0
	v_cmp_le_u32_e32 vcc, 0x100, v45
	s_nop 1
	v_cndmask_b32_e32 v36, v36, v42, vcc
	v_cndmask_b32_e32 v46, v46, v45, vcc
	v_cndmask_b32_e32 v47, v47, v44, vcc
	v_or_b32_e32 v42, 2, v36
	v_lshlrev_b32_e32 v41, v39, v42
	v_add_u32_e64 v43, v34, v41 clamp
	v_mov_b32_e32 v44, 0
	v_cmp_ge_u32_e32 vcc, v0, v43
	v_cmp_ge_u32_e64 s[0:1], v1, v43
	v_cmp_ge_u32_e64 s[2:3], v2, v43
	v_addc_co_u32_e64 v44, vcc, 0, v44, vcc
	v_cmp_ge_u32_e32 vcc, v3, v43
	v_addc_co_u32_e64 v44, s[0:1], 0, v44, s[0:1]
	v_cmp_ge_u32_e64 s[0:1], v4, v43
	v_addc_co_u32_e64 v44, s[2:3], 0, v44, s[2:3]
	v_cmp_ge_u32_e64 s[2:3], v5, v43
	v_addc_co_u32_e64 v44, vcc, 0, v44, vcc
	v_cmp_ge_u32_e32 vcc, v6, v43
	v_addc_co_u32_e64 v44, s[0:1], 0, v44, s[0:1]
	v_cmp_ge_u32_e64 s[0:1], v7, v43
	v_addc_co_u32_e64 v44, s[2:3], 0, v44, s[2:3]
	v_cmp_ge_u32_e64 s[2:3], v8, v43
	v_addc_co_u32_e64 v44, vcc, 0, v44, vcc
	v_cmp_ge_u32_e32 vcc, v9, v43
	v_addc_co_u32_e64 v44, s[0:1], 0, v44, s[0:1]
	v_cmp_ge_u32_e64 s[0:1], v10, v43
	v_addc_co_u32_e64 v44, s[2:3], 0, v44, s[2:3]
	v_cmp_ge_u32_e64 s[2:3], v11, v43
	v_addc_co_u32_e64 v44, vcc, 0, v44, vcc
	v_cmp_ge_u32_e32 vcc, v12, v43
	v_addc_co_u32_e64 v44, s[0:1], 0, v44, s[0:1]
	v_cmp_ge_u32_e64 s[0:1], v13, v43
	v_addc_co_u32_e64 v44, s[2:3], 0, v44, s[2:3]
	v_cmp_ge_u32_e64 s[2:3], v14, v43
	v_addc_co_u32_e64 v44, vcc, 0, v44, vcc
	v_cmp_ge_u32_e32 vcc, v15, v43
	v_addc_co_u32_e64 v44, s[0:1], 0, v44, s[0:1]
	v_cmp_ge_u32_e64 s[0:1], v16, v43
	v_addc_co_u32_e64 v44, s[2:3], 0, v44, s[2:3]
	v_cmp_ge_u32_e64 s[2:3], v17, v43
	v_addc_co_u32_e64 v44, vcc, 0, v44, vcc
	v_cmp_ge_u32_e32 vcc, v18, v43
	v_addc_co_u32_e64 v44, s[0:1], 0, v44, s[0:1]
	v_cmp_ge_u32_e64 s[0:1], v19, v43
	v_addc_co_u32_e64 v44, s[2:3], 0, v44, s[2:3]
	v_cmp_ge_u32_e64 s[2:3], v20, v43
	v_addc_co_u32_e64 v44, vcc, 0, v44, vcc
	v_cmp_ge_u32_e32 vcc, v21, v43
	v_addc_co_u32_e64 v44, s[0:1], 0, v44, s[0:1]
	v_cmp_ge_u32_e64 s[0:1], v22, v43
	v_addc_co_u32_e64 v44, s[2:3], 0, v44, s[2:3]
	v_cmp_ge_u32_e64 s[2:3], v23, v43
	v_addc_co_u32_e64 v44, vcc, 0, v44, vcc
	v_cmp_ge_u32_e32 vcc, v24, v43
	v_addc_co_u32_e64 v44, s[0:1], 0, v44, s[0:1]
	v_cmp_ge_u32_e64 s[0:1], v25, v43
	v_addc_co_u32_e64 v44, s[2:3], 0, v44, s[2:3]
	v_cmp_ge_u32_e64 s[2:3], v26, v43
	v_addc_co_u32_e64 v44, vcc, 0, v44, vcc
	v_cmp_ge_u32_e32 vcc, v27, v43
	v_addc_co_u32_e64 v44, s[0:1], 0, v44, s[0:1]
	v_cmp_ge_u32_e64 s[0:1], v28, v43
	v_addc_co_u32_e64 v44, s[2:3], 0, v44, s[2:3]
	v_cmp_ge_u32_e64 s[2:3], v29, v43
	v_addc_co_u32_e64 v44, vcc, 0, v44, vcc
	v_cmp_ge_u32_e32 vcc, v30, v43
	v_addc_co_u32_e64 v44, s[0:1], 0, v44, s[0:1]
	v_cmp_ge_u32_e64 s[0:1], v31, v43
	v_addc_co_u32_e64 v44, s[2:3], 0, v44, s[2:3]
	v_addc_co_u32_e64 v44, vcc, 0, v44, vcc
	v_addc_co_u32_e64 v44, s[0:1], 0, v44, s[0:1]
	v_mov_b32_e32 v45, v44
	s_nop 1
	v_add_u32_dpp v45, v45, v45 row_ror:1 row_mask:0xf bank_mask:0xf
	s_nop 1
	v_add_u32_dpp v45, v45, v45 row_ror:2 row_mask:0xf bank_mask:0xf
	s_nop 1
	v_add_u32_dpp v45, v45, v45 row_ror:4 row_mask:0xf bank_mask:0xf
	s_nop 1
	v_add_u32_dpp v45, v45, v45 row_ror:8 row_mask:0xf bank_mask:0xf
	s_nop 0
	v_cmp_le_u32_e32 vcc, 0x100, v45
	s_nop 1
	v_cndmask_b32_e32 v36, v36, v42, vcc
	v_cndmask_b32_e32 v46, v46, v45, vcc
	v_cndmask_b32_e32 v47, v47, v44, vcc
	v_or_b32_e32 v42, 1, v36
	v_lshlrev_b32_e32 v41, v39, v42
	v_add_u32_e64 v43, v34, v41 clamp
	v_mov_b32_e32 v44, 0
	v_cmp_ge_u32_e32 vcc, v0, v43
	v_cmp_ge_u32_e64 s[0:1], v1, v43
	v_cmp_ge_u32_e64 s[2:3], v2, v43
	v_addc_co_u32_e64 v44, vcc, 0, v44, vcc
	v_cmp_ge_u32_e32 vcc, v3, v43
	v_addc_co_u32_e64 v44, s[0:1], 0, v44, s[0:1]
	v_cmp_ge_u32_e64 s[0:1], v4, v43
	v_addc_co_u32_e64 v44, s[2:3], 0, v44, s[2:3]
	v_cmp_ge_u32_e64 s[2:3], v5, v43
	v_addc_co_u32_e64 v44, vcc, 0, v44, vcc
	v_cmp_ge_u32_e32 vcc, v6, v43
	v_addc_co_u32_e64 v44, s[0:1], 0, v44, s[0:1]
	v_cmp_ge_u32_e64 s[0:1], v7, v43
	v_addc_co_u32_e64 v44, s[2:3], 0, v44, s[2:3]
	v_cmp_ge_u32_e64 s[2:3], v8, v43
	v_addc_co_u32_e64 v44, vcc, 0, v44, vcc
	v_cmp_ge_u32_e32 vcc, v9, v43
	v_addc_co_u32_e64 v44, s[0:1], 0, v44, s[0:1]
	v_cmp_ge_u32_e64 s[0:1], v10, v43
	v_addc_co_u32_e64 v44, s[2:3], 0, v44, s[2:3]
	v_cmp_ge_u32_e64 s[2:3], v11, v43
	v_addc_co_u32_e64 v44, vcc, 0, v44, vcc
	v_cmp_ge_u32_e32 vcc, v12, v43
	v_addc_co_u32_e64 v44, s[0:1], 0, v44, s[0:1]
	v_cmp_ge_u32_e64 s[0:1], v13, v43
	v_addc_co_u32_e64 v44, s[2:3], 0, v44, s[2:3]
	v_cmp_ge_u32_e64 s[2:3], v14, v43
	v_addc_co_u32_e64 v44, vcc, 0, v44, vcc
	v_cmp_ge_u32_e32 vcc, v15, v43
	v_addc_co_u32_e64 v44, s[0:1], 0, v44, s[0:1]
	v_cmp_ge_u32_e64 s[0:1], v16, v43
	v_addc_co_u32_e64 v44, s[2:3], 0, v44, s[2:3]
	v_cmp_ge_u32_e64 s[2:3], v17, v43
	v_addc_co_u32_e64 v44, vcc, 0, v44, vcc
	v_cmp_ge_u32_e32 vcc, v18, v43
	v_addc_co_u32_e64 v44, s[0:1], 0, v44, s[0:1]
	v_cmp_ge_u32_e64 s[0:1], v19, v43
	v_addc_co_u32_e64 v44, s[2:3], 0, v44, s[2:3]
	v_cmp_ge_u32_e64 s[2:3], v20, v43
	v_addc_co_u32_e64 v44, vcc, 0, v44, vcc
	v_cmp_ge_u32_e32 vcc, v21, v43
	v_addc_co_u32_e64 v44, s[0:1], 0, v44, s[0:1]
	v_cmp_ge_u32_e64 s[0:1], v22, v43
	v_addc_co_u32_e64 v44, s[2:3], 0, v44, s[2:3]
	v_cmp_ge_u32_e64 s[2:3], v23, v43
	v_addc_co_u32_e64 v44, vcc, 0, v44, vcc
	v_cmp_ge_u32_e32 vcc, v24, v43
	v_addc_co_u32_e64 v44, s[0:1], 0, v44, s[0:1]
	v_cmp_ge_u32_e64 s[0:1], v25, v43
	v_addc_co_u32_e64 v44, s[2:3], 0, v44, s[2:3]
	v_cmp_ge_u32_e64 s[2:3], v26, v43
	v_addc_co_u32_e64 v44, vcc, 0, v44, vcc
	v_cmp_ge_u32_e32 vcc, v27, v43
	v_addc_co_u32_e64 v44, s[0:1], 0, v44, s[0:1]
	v_cmp_ge_u32_e64 s[0:1], v28, v43
	v_addc_co_u32_e64 v44, s[2:3], 0, v44, s[2:3]
	v_cmp_ge_u32_e64 s[2:3], v29, v43
	v_addc_co_u32_e64 v44, vcc, 0, v44, vcc
	v_cmp_ge_u32_e32 vcc, v30, v43
	v_addc_co_u32_e64 v44, s[0:1], 0, v44, s[0:1]
	v_cmp_ge_u32_e64 s[0:1], v31, v43
	v_addc_co_u32_e64 v44, s[2:3], 0, v44, s[2:3]
	v_addc_co_u32_e64 v44, vcc, 0, v44, vcc
	v_addc_co_u32_e64 v44, s[0:1], 0, v44, s[0:1]
	v_mov_b32_e32 v45, v44
	s_nop 1
	v_add_u32_dpp v45, v45, v45 row_ror:1 row_mask:0xf bank_mask:0xf
	s_nop 1
	v_add_u32_dpp v45, v45, v45 row_ror:2 row_mask:0xf bank_mask:0xf
	s_nop 1
	v_add_u32_dpp v45, v45, v45 row_ror:4 row_mask:0xf bank_mask:0xf
	s_nop 1
	v_add_u32_dpp v45, v45, v45 row_ror:8 row_mask:0xf bank_mask:0xf
	s_nop 0
	v_cmp_le_u32_e32 vcc, 0x100, v45
	s_nop 1
	v_cndmask_b32_e32 v36, v36, v42, vcc
	v_cndmask_b32_e32 v46, v46, v45, vcc
	v_cndmask_b32_e32 v47, v47, v44, vcc
	v_lshlrev_b32_e32 v41, v39, v36
	v_add_u32_e32 v41, v34, v41
	v_cmp_ge_u32_e32 vcc, 0x140, v46
	v_cmp_eq_u32_e64 s[0:1], 0, v39
	v_lshlrev_b32_e32 v42, v39, v200
	v_add_u32_e32 v42, -1, v42
	s_or_b64 vcc, vcc, s[0:1]
	s_andn2_b64 s[0:1], vcc, s[50:51]
	s_nor_b64 s[2:3], vcc, s[50:51]
	s_or_b64 s[50:51], s[50:51], vcc
	v_add_u32_e64 v42, v41, v42 clamp
	v_min_u32_e32 v42, v42, v35
	v_cndmask_b32_e64 v37, v37, v41, s[0:1]
	v_cndmask_b32_e64 v62, v62, v47, s[0:1]
	v_cndmask_b32_e64 v35, v35, v42, s[2:3]
	v_cndmask_b32_e64 v34, v34, v41, s[2:3]
	s_cmp_eq_u64 s[50:51], -1
	s_cbranch_scc0 .Lp2apr1_iter
	s_mov_b64 exec, s[22:23]
	v_mov_b32_e32 v61, v62
	s_nop 1
	v_add_u32_dpp v61, v61, v61 row_shr:1 row_mask:0xf bank_mask:0xf bound_ctrl:1
	s_nop 1
	v_add_u32_dpp v61, v61, v61 row_shr:2 row_mask:0xf bank_mask:0xf bound_ctrl:1
	s_nop 1
	v_add_u32_dpp v61, v61, v61 row_shr:4 row_mask:0xf bank_mask:0xf bound_ctrl:1
	s_nop 1
	v_add_u32_dpp v61, v61, v61 row_shr:8 row_mask:0xf bank_mask:0xf bound_ctrl:1
	v_sub_u32_e32 v62, v61, v62
	v_cmp_ge_u32_e32 vcc, v0, v37
	v_lshl_add_u32 v41, v62, 2, v59
	s_mov_b64 exec, vcc
	ds_write_b32 v41, v0
	v_add_u32_e32 v62, 1, v62
	s_mov_b64 exec, s[22:23]
	v_cmp_ge_u32_e32 vcc, v1, v37
	v_lshl_add_u32 v41, v62, 2, v59
	s_mov_b64 exec, vcc
	ds_write_b32 v41, v1
	v_add_u32_e32 v62, 1, v62
	s_mov_b64 exec, s[22:23]
	v_cmp_ge_u32_e32 vcc, v2, v37
	v_lshl_add_u32 v41, v62, 2, v59
	s_mov_b64 exec, vcc
	ds_write_b32 v41, v2
	v_add_u32_e32 v62, 1, v62
	s_mov_b64 exec, s[22:23]
	v_cmp_ge_u32_e32 vcc, v3, v37
	v_lshl_add_u32 v41, v62, 2, v59
	s_mov_b64 exec, vcc
	ds_write_b32 v41, v3
	v_add_u32_e32 v62, 1, v62
	s_mov_b64 exec, s[22:23]
	v_cmp_ge_u32_e32 vcc, v4, v37
	v_lshl_add_u32 v41, v62, 2, v59
	s_mov_b64 exec, vcc
	ds_write_b32 v41, v4
	v_add_u32_e32 v62, 1, v62
	s_mov_b64 exec, s[22:23]
	v_cmp_ge_u32_e32 vcc, v5, v37
	v_lshl_add_u32 v41, v62, 2, v59
	s_mov_b64 exec, vcc
	ds_write_b32 v41, v5
	v_add_u32_e32 v62, 1, v62
	s_mov_b64 exec, s[22:23]
	v_cmp_ge_u32_e32 vcc, v6, v37
	v_lshl_add_u32 v41, v62, 2, v59
	s_mov_b64 exec, vcc
	ds_write_b32 v41, v6
	v_add_u32_e32 v62, 1, v62
	s_mov_b64 exec, s[22:23]
	v_cmp_ge_u32_e32 vcc, v7, v37
	v_lshl_add_u32 v41, v62, 2, v59
	s_mov_b64 exec, vcc
	ds_write_b32 v41, v7
	v_add_u32_e32 v62, 1, v62
	s_mov_b64 exec, s[22:23]
	v_cmp_ge_u32_e32 vcc, v8, v37
	v_lshl_add_u32 v41, v62, 2, v59
	s_mov_b64 exec, vcc
	ds_write_b32 v41, v8
	v_add_u32_e32 v62, 1, v62
	s_mov_b64 exec, s[22:23]
	v_cmp_ge_u32_e32 vcc, v9, v37
	v_lshl_add_u32 v41, v62, 2, v59
	s_mov_b64 exec, vcc
	ds_write_b32 v41, v9
	v_add_u32_e32 v62, 1, v62
	s_mov_b64 exec, s[22:23]
	v_cmp_ge_u32_e32 vcc, v10, v37
	v_lshl_add_u32 v41, v62, 2, v59
	s_mov_b64 exec, vcc
	ds_write_b32 v41, v10
	v_add_u32_e32 v62, 1, v62
	s_mov_b64 exec, s[22:23]
	v_cmp_ge_u32_e32 vcc, v11, v37
	v_lshl_add_u32 v41, v62, 2, v59
	s_mov_b64 exec, vcc
	ds_write_b32 v41, v11
	v_add_u32_e32 v62, 1, v62
	s_mov_b64 exec, s[22:23]
	v_cmp_ge_u32_e32 vcc, v12, v37
	v_lshl_add_u32 v41, v62, 2, v59
	s_mov_b64 exec, vcc
	ds_write_b32 v41, v12
	v_add_u32_e32 v62, 1, v62
	s_mov_b64 exec, s[22:23]
	v_cmp_ge_u32_e32 vcc, v13, v37
	v_lshl_add_u32 v41, v62, 2, v59
	s_mov_b64 exec, vcc
	ds_write_b32 v41, v13
	v_add_u32_e32 v62, 1, v62
	s_mov_b64 exec, s[22:23]
	v_cmp_ge_u32_e32 vcc, v14, v37
	v_lshl_add_u32 v41, v62, 2, v59
	s_mov_b64 exec, vcc
	ds_write_b32 v41, v14
	v_add_u32_e32 v62, 1, v62
	s_mov_b64 exec, s[22:23]
	v_cmp_ge_u32_e32 vcc, v15, v37
	v_lshl_add_u32 v41, v62, 2, v59
	s_mov_b64 exec, vcc
	ds_write_b32 v41, v15
	v_add_u32_e32 v62, 1, v62
	s_mov_b64 exec, s[22:23]
	v_cmp_ge_u32_e32 vcc, v16, v37
	v_lshl_add_u32 v41, v62, 2, v59
	s_mov_b64 exec, vcc
	ds_write_b32 v41, v16
	v_add_u32_e32 v62, 1, v62
	s_mov_b64 exec, s[22:23]
	v_cmp_ge_u32_e32 vcc, v17, v37
	v_lshl_add_u32 v41, v62, 2, v59
	s_mov_b64 exec, vcc
	ds_write_b32 v41, v17
	v_add_u32_e32 v62, 1, v62
	s_mov_b64 exec, s[22:23]
	v_cmp_ge_u32_e32 vcc, v18, v37
	v_lshl_add_u32 v41, v62, 2, v59
	s_mov_b64 exec, vcc
	ds_write_b32 v41, v18
	v_add_u32_e32 v62, 1, v62
	s_mov_b64 exec, s[22:23]
	v_cmp_ge_u32_e32 vcc, v19, v37
	v_lshl_add_u32 v41, v62, 2, v59
	s_mov_b64 exec, vcc
	ds_write_b32 v41, v19
	v_add_u32_e32 v62, 1, v62
	s_mov_b64 exec, s[22:23]
	v_cmp_ge_u32_e32 vcc, v20, v37
	v_lshl_add_u32 v41, v62, 2, v59
	s_mov_b64 exec, vcc
	ds_write_b32 v41, v20
	v_add_u32_e32 v62, 1, v62
	s_mov_b64 exec, s[22:23]
	v_cmp_ge_u32_e32 vcc, v21, v37
	v_lshl_add_u32 v41, v62, 2, v59
	s_mov_b64 exec, vcc
	ds_write_b32 v41, v21
	v_add_u32_e32 v62, 1, v62
	s_mov_b64 exec, s[22:23]
	v_cmp_ge_u32_e32 vcc, v22, v37
	v_lshl_add_u32 v41, v62, 2, v59
	s_mov_b64 exec, vcc
	ds_write_b32 v41, v22
	v_add_u32_e32 v62, 1, v62
	s_mov_b64 exec, s[22:23]
	v_cmp_ge_u32_e32 vcc, v23, v37
	v_lshl_add_u32 v41, v62, 2, v59
	s_mov_b64 exec, vcc
	ds_write_b32 v41, v23
	v_add_u32_e32 v62, 1, v62
	s_mov_b64 exec, s[22:23]
	v_cmp_ge_u32_e32 vcc, v24, v37
	v_lshl_add_u32 v41, v62, 2, v59
	s_mov_b64 exec, vcc
	ds_write_b32 v41, v24
	v_add_u32_e32 v62, 1, v62
	s_mov_b64 exec, s[22:23]
	v_cmp_ge_u32_e32 vcc, v25, v37
	v_lshl_add_u32 v41, v62, 2, v59
	s_mov_b64 exec, vcc
	ds_write_b32 v41, v25
	v_add_u32_e32 v62, 1, v62
	s_mov_b64 exec, s[22:23]
	v_cmp_ge_u32_e32 vcc, v26, v37
	v_lshl_add_u32 v41, v62, 2, v59
	s_mov_b64 exec, vcc
	ds_write_b32 v41, v26
	v_add_u32_e32 v62, 1, v62
	s_mov_b64 exec, s[22:23]
	v_cmp_ge_u32_e32 vcc, v27, v37
	v_lshl_add_u32 v41, v62, 2, v59
	s_mov_b64 exec, vcc
	ds_write_b32 v41, v27
	v_add_u32_e32 v62, 1, v62
	s_mov_b64 exec, s[22:23]
	v_cmp_ge_u32_e32 vcc, v28, v37
	v_lshl_add_u32 v41, v62, 2, v59
	s_mov_b64 exec, vcc
	ds_write_b32 v41, v28
	v_add_u32_e32 v62, 1, v62
	s_mov_b64 exec, s[22:23]
	v_cmp_ge_u32_e32 vcc, v29, v37
	v_lshl_add_u32 v41, v62, 2, v59
	s_mov_b64 exec, vcc
	ds_write_b32 v41, v29
	v_add_u32_e32 v62, 1, v62
	s_mov_b64 exec, s[22:23]
	v_cmp_ge_u32_e32 vcc, v30, v37
	v_lshl_add_u32 v41, v62, 2, v59
	s_mov_b64 exec, vcc
	ds_write_b32 v41, v30
	v_add_u32_e32 v62, 1, v62
	s_mov_b64 exec, s[22:23]
	v_cmp_ge_u32_e32 vcc, v31, v37
	v_lshl_add_u32 v41, v62, 2, v59
	s_mov_b64 exec, vcc
	ds_write_b32 v41, v31
	v_add_u32_e32 v62, 1, v62
	s_mov_b64 exec, s[22:23]
	s_mov_b64 exec, -1
	v_and_b32_e32 v41, 0xffffe000, v37
	v_ashrrev_i32_e32 v42, 31, v41
	v_not_b32_e32 v42, v42
	v_or_b32_e32 v42, 0x80000000, v42
	v_xor_b32_e32 v63, v41, v42
	s_cmpk_lt_i32 s8, 0x141
	s_cbranch_scc1 .Lp2apr1_o0
	v_readlane_b32 s0, v63, 0
	v_readlane_b32 s74, v37, 0
	v_readlane_b32 s8, v61, 15
	v_mov_b32_e32 v233, s0
.Lp2apr1_o0:
	s_cmpk_lt_i32 s14, 0x141
	s_cbranch_scc1 .Lp2apr1_o1
	v_readlane_b32 s0, v63, 16
	v_readlane_b32 s75, v37, 16
	v_readlane_b32 s14, v61, 31
	v_mov_b32_e32 v234, s0
.Lp2apr1_o1:
	s_cmpk_lt_i32 s13, 0x141
	s_cbranch_scc1 .Lp2apr1_o2
	v_readlane_b32 s0, v63, 32
	v_readlane_b32 s76, v37, 32
	v_readlane_b32 s13, v61, 47
	v_mov_b32_e32 v235, s0
.Lp2apr1_o2:
	s_cmpk_lt_i32 s5, 0x141
	s_cbranch_scc1 .Lp2apr1_o3
	v_readlane_b32 s0, v63, 48
	v_readlane_b32 s77, v37, 48
	v_readlane_b32 s5, v61, 63
	v_mov_b32_e32 v236, s0
.Lp2apr1_o3:
.Lp2apr1_end:
.LBB0_1045:
	s_add_i32 s66, s66, 64
	v_subrev_u32_e32 v228, 64, v228
	s_and_b64 vcc, exec, s[6:7]
	s_cbranch_vccnz .LBB0_1066
.LBB0_1046:
	s_mov_b32 s9, s69
	s_branch .LBB0_577
.LBB0_1066:
	s_and_b32 s0, s73, 0xffffe000
	s_and_b32 s66, s72, 0xffffe000
	s_and_b32 s63, s71, 0xffffe000
	s_and_b32 s51, s70, 0xffffe000
	s_and_b32 s50, s74, 0xffffe000
	s_and_b32 s23, s75, 0xffffe000
	s_and_b32 s22, s76, 0xffffe000
	s_and_b32 s9, s77, 0xffffe000
	s_andn2_b64 vcc, exec, s[64:65]
	s_cbranch_vccnz .LBB0_567
	s_branch .LBB0_1068

.LBB0_1647:
	v_add_u32_e32 v74, s2, v152
	v_mov_b32_e32 v169, v65
	s_add_i32 s9, s9, s5
	s_add_i32 s2, s2, s3
	v_mov_b32_e32 v124, 0x1600
	v_mad_u32_u24 v72, v74, v124, v64
	v_lshl_add_u32 v75, v74, 11, v64
	v_add_u32_e32 v73, 64, v72
	s_add_u32 s0, s6, 0x1200
	s_addc_u32 s1, s7, 0
	global_load_dword v92, v[154:155], off
	global_load_ushort v76, v72, s[0:1]
	global_load_ushort v77, v73, s[0:1]
	s_add_u32 s0, s6, 0x2800
	s_addc_u32 s1, s7, 0
	global_load_dword v93, v[156:157], off offset:4
	global_load_ushort v78, v72, s[0:1]
	global_load_ushort v79, v73, s[0:1]
	s_add_u32 s0, s6, 0x3e00
	s_addc_u32 s1, s7, 0
	global_load_dword v94, v[156:157], off offset:8
	global_load_ushort v80, v72, s[0:1]
	global_load_ushort v81, v73, s[0:1]
	s_add_u32 s0, s6, 0x5400
	s_addc_u32 s1, s7, 0
	global_load_dword v95, v[156:157], off offset:12
	global_load_ushort v82, v72, s[0:1]
	global_load_ushort v83, v73, s[0:1]
	s_add_u32 s0, s6, 0xc200
	s_addc_u32 s1, s7, 0
	global_load_dword v96, v[156:157], off offset:32
	global_load_ushort v84, v72, s[0:1]
	global_load_ushort v85, v73, s[0:1]
	s_add_u32 s0, s6, 0xd800
	s_addc_u32 s1, s7, 0
	global_load_dword v97, v[156:157], off offset:36
	global_load_ushort v86, v72, s[0:1]
	global_load_ushort v87, v73, s[0:1]
	s_add_u32 s0, s6, 0xee00
	s_addc_u32 s1, s7, 0
	global_load_dword v98, v[156:157], off offset:40
	global_load_ushort v88, v72, s[0:1]
	global_load_ushort v89, v73, s[0:1]
	s_add_u32 s0, s6, 0x10400
	s_addc_u32 s1, s7, 0
	global_load_dword v99, v[156:157], off offset:44
	global_load_ushort v90, v72, s[0:1]
	global_load_ushort v91, v73, s[0:1]
	s_add_u32 s0, s6, 0x17200
	s_addc_u32 s1, s7, 0
	global_load_dword v116, v[156:157], off offset:64
	global_load_ushort v100, v72, s[0:1]
	global_load_ushort v101, v73, s[0:1]
	s_add_u32 s0, s6, 0x18800
	s_addc_u32 s1, s7, 0
	global_load_dword v117, v[156:157], off offset:68
	global_load_ushort v102, v72, s[0:1]
	global_load_ushort v103, v73, s[0:1]
	s_add_u32 s0, s6, 0x19e00
	s_addc_u32 s1, s7, 0
	global_load_dword v118, v[156:157], off offset:72
	global_load_ushort v104, v72, s[0:1]
	global_load_ushort v105, v73, s[0:1]
	s_add_u32 s0, s6, 0x1b400
	s_addc_u32 s1, s7, 0
	global_load_dword v119, v[156:157], off offset:76
	global_load_ushort v106, v72, s[0:1]
	global_load_ushort v107, v73, s[0:1]
	s_add_u32 s0, s6, 0x22200
	s_addc_u32 s1, s7, 0
	global_load_dword v120, v[156:157], off offset:96
	global_load_ushort v108, v72, s[0:1]
	global_load_ushort v109, v73, s[0:1]
	s_add_u32 s0, s6, 0x23800
	s_addc_u32 s1, s7, 0
	global_load_dword v121, v[156:157], off offset:100
	global_load_ushort v110, v72, s[0:1]
	global_load_ushort v111, v73, s[0:1]
	s_add_u32 s0, s6, 0x24e00
	s_addc_u32 s1, s7, 0
	global_load_dword v122, v[156:157], off offset:104
	global_load_ushort v112, v72, s[0:1]
	global_load_ushort v113, v73, s[0:1]
	s_add_u32 s0, s6, 0x26400
	s_addc_u32 s1, s7, 0
	global_load_dword v123, v[156:157], off offset:108
	global_load_ushort v114, v72, s[0:1]
	global_load_ushort v115, v73, s[0:1]
	s_waitcnt vmcnt(24)
	s_add_u32 s10, s60, 0x0
	s_addc_u32 s11, s61, 0
	v_add_f32_e32 v48, v92, v48
	v_add_f32_e32 v32, v32, v92
	v_lshlrev_b32_e32 v76, 16, v76
	v_lshlrev_b32_e32 v77, 16, v77
	v_mul_f32_e32 v48, v48, v76
	v_mul_f32_e32 v32, v32, v77
	v_cvt_pk_bf16_f32 v48, v48, v65
	v_cvt_pk_bf16_f32 v32, v32, v65
	global_store_short v75, v48, s[10:11] offset:1536
	global_store_short v75, v32, s[10:11] offset:1600
	s_add_u32 s10, s60, 0x800
	s_addc_u32 s11, s61, 0
	v_add_f32_e32 v49, v93, v49
	v_add_f32_e32 v33, v33, v93
	v_lshlrev_b32_e32 v78, 16, v78
	v_lshlrev_b32_e32 v79, 16, v79
	v_mul_f32_e32 v49, v49, v78
	v_mul_f32_e32 v33, v33, v79
	v_cvt_pk_bf16_f32 v49, v49, v65
	v_cvt_pk_bf16_f32 v33, v33, v65
	global_store_short v75, v49, s[10:11] offset:1536
	global_store_short v75, v33, s[10:11] offset:1600
	s_add_u32 s10, s60, 0x1000
	s_addc_u32 s11, s61, 0
	v_add_f32_e32 v50, v94, v50
	v_add_f32_e32 v34, v34, v94
	v_lshlrev_b32_e32 v80, 16, v80
	v_lshlrev_b32_e32 v81, 16, v81
	v_mul_f32_e32 v50, v50, v80
	v_mul_f32_e32 v34, v34, v81
	v_cvt_pk_bf16_f32 v50, v50, v65
	v_cvt_pk_bf16_f32 v34, v34, v65
	global_store_short v75, v50, s[10:11] offset:1536
	global_store_short v75, v34, s[10:11] offset:1600
	s_add_u32 s10, s60, 0x1800
	s_addc_u32 s11, s61, 0
	v_add_f32_e32 v51, v95, v51
	v_add_f32_e32 v35, v35, v95
	v_lshlrev_b32_e32 v82, 16, v82
	v_lshlrev_b32_e32 v83, 16, v83
	v_mul_f32_e32 v51, v51, v82
	v_mul_f32_e32 v35, v35, v83
	v_cvt_pk_bf16_f32 v51, v51, v65
	v_cvt_pk_bf16_f32 v35, v35, v65
	global_store_short v75, v51, s[10:11] offset:1536
	global_store_short v75, v35, s[10:11] offset:1600
	s_add_u32 s10, s60, 0x4000
	s_addc_u32 s11, s61, 0
	v_add_f32_e32 v52, v96, v52
	v_add_f32_e32 v36, v36, v96
	v_lshlrev_b32_e32 v84, 16, v84
	v_lshlrev_b32_e32 v85, 16, v85
	v_mul_f32_e32 v52, v52, v84
	v_mul_f32_e32 v36, v36, v85
	v_cvt_pk_bf16_f32 v52, v52, v65
	v_cvt_pk_bf16_f32 v36, v36, v65
	global_store_short v75, v52, s[10:11] offset:1536
	global_store_short v75, v36, s[10:11] offset:1600
	s_add_u32 s10, s60, 0x4800
	s_addc_u32 s11, s61, 0
	v_add_f32_e32 v53, v97, v53
	v_add_f32_e32 v37, v37, v97
	v_lshlrev_b32_e32 v86, 16, v86
	v_lshlrev_b32_e32 v87, 16, v87
	v_mul_f32_e32 v53, v53, v86
	v_mul_f32_e32 v37, v37, v87
	v_cvt_pk_bf16_f32 v53, v53, v65
	v_cvt_pk_bf16_f32 v37, v37, v65
	global_store_short v75, v53, s[10:11] offset:1536
	global_store_short v75, v37, s[10:11] offset:1600
	s_add_u32 s10, s60, 0x5000
	s_addc_u32 s11, s61, 0
	v_add_f32_e32 v54, v98, v54
	v_add_f32_e32 v38, v38, v98
	v_lshlrev_b32_e32 v88, 16, v88
	v_lshlrev_b32_e32 v89, 16, v89
	v_mul_f32_e32 v54, v54, v88
	v_mul_f32_e32 v38, v38, v89
	v_cvt_pk_bf16_f32 v54, v54, v65
	v_cvt_pk_bf16_f32 v38, v38, v65
	global_store_short v75, v54, s[10:11] offset:1536
	global_store_short v75, v38, s[10:11] offset:1600
	s_add_u32 s10, s60, 0x5800
	s_addc_u32 s11, s61, 0
	v_add_f32_e32 v55, v99, v55
	v_add_f32_e32 v39, v39, v99
	v_lshlrev_b32_e32 v90, 16, v90
	v_lshlrev_b32_e32 v91, 16, v91
	v_mul_f32_e32 v55, v55, v90
	v_mul_f32_e32 v39, v39, v91
	v_cvt_pk_bf16_f32 v55, v55, v65
	v_cvt_pk_bf16_f32 v39, v39, v65
	global_store_short v75, v55, s[10:11] offset:1536
	global_store_short v75, v39, s[10:11] offset:1600
	s_add_u32 s0, s6, 0x2d200
	s_addc_u32 s1, s7, 0
	global_load_dword v92, v[156:157], off offset:128
	global_load_ushort v76, v72, s[0:1]
	global_load_ushort v77, v73, s[0:1]
	s_add_u32 s0, s6, 0x2e800
	s_addc_u32 s1, s7, 0
	global_load_dword v93, v[156:157], off offset:132
	global_load_ushort v78, v72, s[0:1]
	global_load_ushort v79, v73, s[0:1]
	s_add_u32 s0, s6, 0x2fe00
	s_addc_u32 s1, s7, 0
	global_load_dword v94, v[156:157], off offset:136
	global_load_ushort v80, v72, s[0:1]
	global_load_ushort v81, v73, s[0:1]
	s_add_u32 s0, s6, 0x31400
	s_addc_u32 s1, s7, 0
	global_load_dword v95, v[156:157], off offset:140
	global_load_ushort v82, v72, s[0:1]
	global_load_ushort v83, v73, s[0:1]
	s_add_u32 s0, s6, 0x38200
	s_addc_u32 s1, s7, 0
	global_load_dword v96, v[156:157], off offset:160
	global_load_ushort v84, v72, s[0:1]
	global_load_ushort v85, v73, s[0:1]
	s_add_u32 s0, s6, 0x39800
	s_addc_u32 s1, s7, 0
	global_load_dword v97, v[156:157], off offset:164
	global_load_ushort v86, v72, s[0:1]
	global_load_ushort v87, v73, s[0:1]
	s_add_u32 s0, s6, 0x3ae00
	s_addc_u32 s1, s7, 0
	global_load_dword v98, v[156:157], off offset:168
	global_load_ushort v88, v72, s[0:1]
	global_load_ushort v89, v73, s[0:1]
	s_add_u32 s0, s6, 0x3c400
	s_addc_u32 s1, s7, 0
	global_load_dword v99, v[156:157], off offset:172
	global_load_ushort v90, v72, s[0:1]
	global_load_ushort v91, v73, s[0:1]
	s_waitcnt vmcnt(40)
	s_add_u32 s10, s60, 0x8000
	s_addc_u32 s11, s61, 0
	v_add_f32_e32 v56, v116, v56
	v_add_f32_e32 v40, v40, v116
	v_lshlrev_b32_e32 v100, 16, v100
	v_lshlrev_b32_e32 v101, 16, v101
	v_mul_f32_e32 v56, v56, v100
	v_mul_f32_e32 v40, v40, v101
	v_cvt_pk_bf16_f32 v56, v56, v65
	v_cvt_pk_bf16_f32 v40, v40, v65
	global_store_short v75, v56, s[10:11] offset:1536
	global_store_short v75, v40, s[10:11] offset:1600
	s_add_u32 s10, s60, 0x8800
	s_addc_u32 s11, s61, 0
	v_add_f32_e32 v57, v117, v57
	v_add_f32_e32 v41, v41, v117
	v_lshlrev_b32_e32 v102, 16, v102
	v_lshlrev_b32_e32 v103, 16, v103
	v_mul_f32_e32 v57, v57, v102
	v_mul_f32_e32 v41, v41, v103
	v_cvt_pk_bf16_f32 v57, v57, v65
	v_cvt_pk_bf16_f32 v41, v41, v65
	global_store_short v75, v57, s[10:11] offset:1536
	global_store_short v75, v41, s[10:11] offset:1600
	s_add_u32 s10, s60, 0x9000
	s_addc_u32 s11, s61, 0
	v_add_f32_e32 v58, v118, v58
	v_add_f32_e32 v42, v42, v118
	v_lshlrev_b32_e32 v104, 16, v104
	v_lshlrev_b32_e32 v105, 16, v105
	v_mul_f32_e32 v58, v58, v104
	v_mul_f32_e32 v42, v42, v105
	v_cvt_pk_bf16_f32 v58, v58, v65
	v_cvt_pk_bf16_f32 v42, v42, v65
	global_store_short v75, v58, s[10:11] offset:1536
	global_store_short v75, v42, s[10:11] offset:1600
	s_add_u32 s10, s60, 0x9800
	s_addc_u32 s11, s61, 0
	v_add_f32_e32 v59, v119, v59
	v_add_f32_e32 v43, v43, v119
	v_lshlrev_b32_e32 v106, 16, v106
	v_lshlrev_b32_e32 v107, 16, v107
	v_mul_f32_e32 v59, v59, v106
	v_mul_f32_e32 v43, v43, v107
	v_cvt_pk_bf16_f32 v59, v59, v65
	v_cvt_pk_bf16_f32 v43, v43, v65
	global_store_short v75, v59, s[10:11] offset:1536
	global_store_short v75, v43, s[10:11] offset:1600
	s_add_u32 s10, s60, 0xc000
	s_addc_u32 s11, s61, 0
	v_add_f32_e32 v60, v120, v60
	v_add_f32_e32 v44, v44, v120
	v_lshlrev_b32_e32 v108, 16, v108
	v_lshlrev_b32_e32 v109, 16, v109
	v_mul_f32_e32 v60, v60, v108
	v_mul_f32_e32 v44, v44, v109
	v_cvt_pk_bf16_f32 v60, v60, v65
	v_cvt_pk_bf16_f32 v44, v44, v65
	global_store_short v75, v60, s[10:11] offset:1536
	global_store_short v75, v44, s[10:11] offset:1600
	s_add_u32 s10, s60, 0xc800
	s_addc_u32 s11, s61, 0
	v_add_f32_e32 v61, v121, v61
	v_add_f32_e32 v45, v45, v121
	v_lshlrev_b32_e32 v110, 16, v110
	v_lshlrev_b32_e32 v111, 16, v111
	v_mul_f32_e32 v61, v61, v110
	v_mul_f32_e32 v45, v45, v111
	v_cvt_pk_bf16_f32 v61, v61, v65
	v_cvt_pk_bf16_f32 v45, v45, v65
	global_store_short v75, v61, s[10:11] offset:1536
	global_store_short v75, v45, s[10:11] offset:1600
	s_add_u32 s10, s60, 0xd000
	s_addc_u32 s11, s61, 0
	v_add_f32_e32 v62, v122, v62
	v_add_f32_e32 v46, v46, v122
	v_lshlrev_b32_e32 v112, 16, v112
	v_lshlrev_b32_e32 v113, 16, v113
	v_mul_f32_e32 v62, v62, v112
	v_mul_f32_e32 v46, v46, v113
	v_cvt_pk_bf16_f32 v62, v62, v65
	v_cvt_pk_bf16_f32 v46, v46, v65
	global_store_short v75, v62, s[10:11] offset:1536
	global_store_short v75, v46, s[10:11] offset:1600
	s_add_u32 s10, s60, 0xd800
	s_addc_u32 s11, s61, 0
	v_add_f32_e32 v63, v123, v63
	v_add_f32_e32 v47, v47, v123
	v_lshlrev_b32_e32 v114, 16, v114
	v_lshlrev_b32_e32 v115, 16, v115
	v_mul_f32_e32 v63, v63, v114
	v_mul_f32_e32 v47, v47, v115
	v_cvt_pk_bf16_f32 v63, v63, v65
	v_cvt_pk_bf16_f32 v47, v47, v65
	global_store_short v75, v63, s[10:11] offset:1536
	global_store_short v75, v47, s[10:11] offset:1600
	s_add_u32 s0, s6, 0x43200
	s_addc_u32 s1, s7, 0
	global_load_dword v116, v[156:157], off offset:192
	global_load_ushort v100, v72, s[0:1]
	global_load_ushort v101, v73, s[0:1]
	s_add_u32 s0, s6, 0x44800
	s_addc_u32 s1, s7, 0
	global_load_dword v117, v[156:157], off offset:196
	global_load_ushort v102, v72, s[0:1]
	global_load_ushort v103, v73, s[0:1]
	s_add_u32 s0, s6, 0x45e00
	s_addc_u32 s1, s7, 0
	global_load_dword v118, v[156:157], off offset:200
	global_load_ushort v104, v72, s[0:1]
	global_load_ushort v105, v73, s[0:1]
	s_add_u32 s0, s6, 0x47400
	s_addc_u32 s1, s7, 0
	global_load_dword v119, v[156:157], off offset:204
	global_load_ushort v106, v72, s[0:1]
	global_load_ushort v107, v73, s[0:1]
	s_add_u32 s0, s6, 0x4e200
	s_addc_u32 s1, s7, 0
	global_load_dword v120, v[156:157], off offset:224
	global_load_ushort v108, v72, s[0:1]
	global_load_ushort v109, v73, s[0:1]
	s_add_u32 s0, s6, 0x4f800
	s_addc_u32 s1, s7, 0
	global_load_dword v121, v[156:157], off offset:228
	global_load_ushort v110, v72, s[0:1]
	global_load_ushort v111, v73, s[0:1]
	s_add_u32 s0, s6, 0x50e00
	s_addc_u32 s1, s7, 0
	global_load_dword v122, v[156:157], off offset:232
	global_load_ushort v112, v72, s[0:1]
	global_load_ushort v113, v73, s[0:1]
	s_add_u32 s0, s6, 0x52400
	s_addc_u32 s1, s7, 0
	global_load_dword v123, v[156:157], off offset:236
	global_load_ushort v114, v72, s[0:1]
	global_load_ushort v115, v73, s[0:1]
	s_waitcnt vmcnt(40)
	s_add_u32 s10, s60, 0x10000
	s_addc_u32 s11, s61, 0
	v_add_f32_e32 v16, v92, v16
	v_add_f32_e32 v0, v0, v92
	v_lshlrev_b32_e32 v76, 16, v76
	v_lshlrev_b32_e32 v77, 16, v77
	v_mul_f32_e32 v16, v16, v76
	v_mul_f32_e32 v0, v0, v77
	v_cvt_pk_bf16_f32 v16, v16, v65
	v_cvt_pk_bf16_f32 v0, v0, v65
	global_store_short v75, v16, s[10:11] offset:1536
	global_store_short v75, v0, s[10:11] offset:1600
	s_add_u32 s10, s60, 0x10800
	s_addc_u32 s11, s61, 0
	v_add_f32_e32 v17, v93, v17
	v_add_f32_e32 v1, v1, v93
	v_lshlrev_b32_e32 v78, 16, v78
	v_lshlrev_b32_e32 v79, 16, v79
	v_mul_f32_e32 v17, v17, v78
	v_mul_f32_e32 v1, v1, v79
	v_cvt_pk_bf16_f32 v17, v17, v65
	v_cvt_pk_bf16_f32 v1, v1, v65
	global_store_short v75, v17, s[10:11] offset:1536
	global_store_short v75, v1, s[10:11] offset:1600
	s_add_u32 s10, s60, 0x11000
	s_addc_u32 s11, s61, 0
	v_add_f32_e32 v18, v94, v18
	v_add_f32_e32 v2, v2, v94
	v_lshlrev_b32_e32 v80, 16, v80
	v_lshlrev_b32_e32 v81, 16, v81
	v_mul_f32_e32 v18, v18, v80
	v_mul_f32_e32 v2, v2, v81
	v_cvt_pk_bf16_f32 v18, v18, v65
	v_cvt_pk_bf16_f32 v2, v2, v65
	global_store_short v75, v18, s[10:11] offset:1536
	global_store_short v75, v2, s[10:11] offset:1600
	s_add_u32 s10, s60, 0x11800
	s_addc_u32 s11, s61, 0
	v_add_f32_e32 v19, v95, v19
	v_add_f32_e32 v3, v3, v95
	v_lshlrev_b32_e32 v82, 16, v82
	v_lshlrev_b32_e32 v83, 16, v83
	v_mul_f32_e32 v19, v19, v82
	v_mul_f32_e32 v3, v3, v83
	v_cvt_pk_bf16_f32 v19, v19, v65
	v_cvt_pk_bf16_f32 v3, v3, v65
	global_store_short v75, v19, s[10:11] offset:1536
	global_store_short v75, v3, s[10:11] offset:1600
	s_add_u32 s10, s60, 0x14000
	s_addc_u32 s11, s61, 0
	v_add_f32_e32 v20, v96, v20
	v_add_f32_e32 v4, v4, v96
	v_lshlrev_b32_e32 v84, 16, v84
	v_lshlrev_b32_e32 v85, 16, v85
	v_mul_f32_e32 v20, v20, v84
	v_mul_f32_e32 v4, v4, v85
	v_cvt_pk_bf16_f32 v20, v20, v65
	v_cvt_pk_bf16_f32 v4, v4, v65
	global_store_short v75, v20, s[10:11] offset:1536
	global_store_short v75, v4, s[10:11] offset:1600
	s_add_u32 s10, s60, 0x14800
	s_addc_u32 s11, s61, 0
	v_add_f32_e32 v21, v97, v21
	v_add_f32_e32 v5, v5, v97
	v_lshlrev_b32_e32 v86, 16, v86
	v_lshlrev_b32_e32 v87, 16, v87
	v_mul_f32_e32 v21, v21, v86
	v_mul_f32_e32 v5, v5, v87
	v_cvt_pk_bf16_f32 v21, v21, v65
	v_cvt_pk_bf16_f32 v5, v5, v65
	global_store_short v75, v21, s[10:11] offset:1536
	global_store_short v75, v5, s[10:11] offset:1600
	s_add_u32 s10, s60, 0x15000
	s_addc_u32 s11, s61, 0
	v_add_f32_e32 v22, v98, v22
	v_add_f32_e32 v6, v6, v98
	v_lshlrev_b32_e32 v88, 16, v88
	v_lshlrev_b32_e32 v89, 16, v89
	v_mul_f32_e32 v22, v22, v88
	v_mul_f32_e32 v6, v6, v89
	v_cvt_pk_bf16_f32 v22, v22, v65
	v_cvt_pk_bf16_f32 v6, v6, v65
	global_store_short v75, v22, s[10:11] offset:1536
	global_store_short v75, v6, s[10:11] offset:1600
	s_add_u32 s10, s60, 0x15800
	s_addc_u32 s11, s61, 0
	v_add_f32_e32 v23, v99, v23
	v_add_f32_e32 v7, v7, v99
	v_lshlrev_b32_e32 v90, 16, v90
	v_lshlrev_b32_e32 v91, 16, v91
	v_mul_f32_e32 v23, v23, v90
	v_mul_f32_e32 v7, v7, v91
	v_cvt_pk_bf16_f32 v23, v23, v65
	v_cvt_pk_bf16_f32 v7, v7, v65
	global_store_short v75, v23, s[10:11] offset:1536
	global_store_short v75, v7, s[10:11] offset:1600
	s_waitcnt vmcnt(16)
	s_add_u32 s10, s60, 0x18000
	s_addc_u32 s11, s61, 0
	v_add_f32_e32 v24, v116, v24
	v_add_f32_e32 v8, v8, v116
	v_lshlrev_b32_e32 v100, 16, v100
	v_lshlrev_b32_e32 v101, 16, v101
	v_mul_f32_e32 v24, v24, v100
	v_mul_f32_e32 v8, v8, v101
	v_cvt_pk_bf16_f32 v24, v24, v65
	v_cvt_pk_bf16_f32 v8, v8, v65
	global_store_short v75, v24, s[10:11] offset:1536
	global_store_short v75, v8, s[10:11] offset:1600
	s_add_u32 s10, s60, 0x18800
	s_addc_u32 s11, s61, 0
	v_add_f32_e32 v25, v117, v25
	v_add_f32_e32 v9, v9, v117
	v_lshlrev_b32_e32 v102, 16, v102
	v_lshlrev_b32_e32 v103, 16, v103
	v_mul_f32_e32 v25, v25, v102
	v_mul_f32_e32 v9, v9, v103
	v_cvt_pk_bf16_f32 v25, v25, v65
	v_cvt_pk_bf16_f32 v9, v9, v65
	global_store_short v75, v25, s[10:11] offset:1536
	global_store_short v75, v9, s[10:11] offset:1600
	s_add_u32 s10, s60, 0x19000
	s_addc_u32 s11, s61, 0
	v_add_f32_e32 v26, v118, v26
	v_add_f32_e32 v10, v10, v118
	v_lshlrev_b32_e32 v104, 16, v104
	v_lshlrev_b32_e32 v105, 16, v105
	v_mul_f32_e32 v26, v26, v104
	v_mul_f32_e32 v10, v10, v105
	v_cvt_pk_bf16_f32 v26, v26, v65
	v_cvt_pk_bf16_f32 v10, v10, v65
	global_store_short v75, v26, s[10:11] offset:1536
	global_store_short v75, v10, s[10:11] offset:1600
	s_add_u32 s10, s60, 0x19800
	s_addc_u32 s11, s61, 0
	v_add_f32_e32 v27, v119, v27
	v_add_f32_e32 v11, v11, v119
	v_lshlrev_b32_e32 v106, 16, v106
	v_lshlrev_b32_e32 v107, 16, v107
	v_mul_f32_e32 v27, v27, v106
	v_mul_f32_e32 v11, v11, v107
	v_cvt_pk_bf16_f32 v27, v27, v65
	v_cvt_pk_bf16_f32 v11, v11, v65
	global_store_short v75, v27, s[10:11] offset:1536
	global_store_short v75, v11, s[10:11] offset:1600
	s_add_u32 s10, s60, 0x1c000
	s_addc_u32 s11, s61, 0
	v_add_f32_e32 v28, v120, v28
	v_add_f32_e32 v12, v12, v120
	v_lshlrev_b32_e32 v108, 16, v108
	v_lshlrev_b32_e32 v109, 16, v109
	v_mul_f32_e32 v28, v28, v108
	v_mul_f32_e32 v12, v12, v109
	v_cvt_pk_bf16_f32 v28, v28, v65
	v_cvt_pk_bf16_f32 v12, v12, v65
	global_store_short v75, v28, s[10:11] offset:1536
	global_store_short v75, v12, s[10:11] offset:1600
	s_add_u32 s10, s60, 0x1c800
	s_addc_u32 s11, s61, 0
	v_add_f32_e32 v29, v121, v29
	v_add_f32_e32 v13, v13, v121
	v_lshlrev_b32_e32 v110, 16, v110
	v_lshlrev_b32_e32 v111, 16, v111
	v_mul_f32_e32 v29, v29, v110
	v_mul_f32_e32 v13, v13, v111
	v_cvt_pk_bf16_f32 v29, v29, v65
	v_cvt_pk_bf16_f32 v13, v13, v65
	global_store_short v75, v29, s[10:11] offset:1536
	global_store_short v75, v13, s[10:11] offset:1600
	s_add_u32 s10, s60, 0x1d000
	s_addc_u32 s11, s61, 0
	v_add_f32_e32 v30, v122, v30
	v_add_f32_e32 v14, v14, v122
	v_lshlrev_b32_e32 v112, 16, v112
	v_lshlrev_b32_e32 v113, 16, v113
	v_mul_f32_e32 v30, v30, v112
	v_mul_f32_e32 v14, v14, v113
	v_cvt_pk_bf16_f32 v30, v30, v65
	v_cvt_pk_bf16_f32 v14, v14, v65
	global_store_short v75, v30, s[10:11] offset:1536
	global_store_short v75, v14, s[10:11] offset:1600
	s_add_u32 s10, s60, 0x1d800
	s_addc_u32 s11, s61, 0
	v_add_f32_e32 v31, v123, v31
	v_add_f32_e32 v15, v15, v123
	v_lshlrev_b32_e32 v114, 16, v114
	v_lshlrev_b32_e32 v115, 16, v115
	v_mul_f32_e32 v31, v31, v114
	v_mul_f32_e32 v15, v15, v115
	v_cvt_pk_bf16_f32 v31, v31, v65
	v_cvt_pk_bf16_f32 v15, v15, v65
	global_store_short v75, v31, s[10:11] offset:1536
	global_store_short v75, v15, s[10:11] offset:1600
	s_cmpk_lt_i32 s9, 0x80
	s_waitcnt lgkmcnt(0)
	s_barrier
	s_cbranch_scc0 .LBB0_1656
